# prologue transposes and rwkv item preambles: loads unrolled into flight; gate GEMM epilogue yb loads batched; hgrn i-tile loads hoisted
# speedup vs baseline: 1.0810x; 1.0058x over previous
; __device__ __forceinline__ float bf2f(unsigned short v) { return __uint_as_float(((unsigned)v) << 16); }
; __device__ __forceinline__ float sigmoidf_(float x) { return __builtin_amdgcn_rcpf(1.0f + __expf(-x)); }
; template <bool PA>
; __device__ __forceinline__ void hgrn_scan(unsigned char* lds, const bf16* Q, const bf16* FFb, const bf16* FBb, const bf16* Ib, bf16* OFb, bf16* OBb, const float* lbp, float* segm, int slab, int tid) {
;     ...
;             float bl[16], kvv[16], qv[16]; float run = 1.f;
; #pragma unroll
;             for (int jj = 0; jj < 16; ++jj) { const float f = bf2f(fraw[jj]); const float fg = lb + (1.0f - lb) * sigmoidf_(f); run *= fg; bl[jj] = run; kvv[jj] = 1.0f - fg; qv[jj] = bf2f(qraw[jj]); }
;             tot[seg * 128 + c] = run;
;             { const size_t row = cbase + (dir ? 63 - jr : jr);
;               const u32x4_t w0 = *(const u32x4_t*)(Ib + row * 1024 + head * 128 + part * 16), w1 = *(const u32x4_t*)(Ib + row * 1024 + head * 128 + part * 16 + 8);
;               const unsigned wa[8] = {w0.x, w0.y, w0.z, w0.w, w1.x, w1.y, w1.z, w1.w};
; #pragma unroll
;               for (int q = 0; q < 8; ++q) { iT[(part * 16 + 2 * q) * 72 + jr] = (bf16)(wa[q] & 0xffff); iT[(part * 16 + 2 * q + 1) * 72 + jr] = (bf16)(wa[q] >> 16); } }
;             if (p + 1 < p1) { const int nb = seqbase + (dir ? nch - 2 - p : p + 1) * 64;
; #pragma unroll
;                 for (int jj = 0; jj < 16; ++jj) { const int j = 16 * seg + jj; const unsigned bo = ((unsigned)(nb + (dir ? 63 - j : j)) * 1024u + (unsigned)hc) * 2u; qraw[jj] = PA ? (unsigned short)0 : *(const unsigned short*)((const char*)Q + bo); fraw[jj] = *(const unsigned short*)((const char*)Fp + bo); } }
.LBB0_68:
	s_waitcnt vmcnt(15)
	v_lshlrev_b32_e32 v0, 16, v156
	v_mul_f32_e32 v0, 0xbfb8aa3b, v0
	v_exp_f32_e32 v0, v0
	s_add_i32 s12, s24, 1
	s_and_b64 s[10:11], s[40:41], exec
	s_cselect_b32 s10, s49, s12
	v_lshl_add_u32 v204, s10, 6, v166
	v_ashrrev_i32_e32 v205, 31, v204
	v_lshlrev_b64 v[204:205], 11, v[204:205]
	v_lshl_add_u64 v[204:205], v[62:63], 0, v[204:205]
	global_load_dwordx4 v[208:211], v[204:205], off
	global_load_dwordx4 v[212:215], v[204:205], off offset:16
	v_add_f32_e32 v0, 1.0, v0
	v_rcp_f32_e32 v2, v0
	s_waitcnt vmcnt(16)
	v_lshlrev_b32_e32 v0, 16, v157
	v_mul_f32_e32 v0, 0xbfb8aa3b, v0
	v_exp_f32_e32 v0, v0
	s_add_i32 s49, s49, 1
	s_cmp_ge_i32 s49, s50
	v_add_f32_e32 v0, 1.0, v0
	v_rcp_f32_e32 v3, v0
	s_waitcnt vmcnt(15)
	v_lshlrev_b32_e32 v0, 16, v159
	v_mul_f32_e32 v0, 0xbfb8aa3b, v0
	v_exp_f32_e32 v0, v0
	v_pk_fma_f32 v[76:77], v[58:59], v[2:3], v[56:57]
	v_add_f32_e32 v0, 1.0, v0
	v_rcp_f32_e32 v4, v0
	s_waitcnt vmcnt(14)
	v_lshlrev_b32_e32 v0, 16, v160
	v_mul_f32_e32 v0, 0xbfb8aa3b, v0
	v_exp_f32_e32 v0, v0
	v_mul_f32_e32 v73, v76, v77
	v_add_f32_e32 v0, 1.0, v0
	v_rcp_f32_e32 v5, v0
	s_waitcnt vmcnt(13)
	v_lshlrev_b32_e32 v0, 16, v162
	v_mul_f32_e32 v0, 0xbfb8aa3b, v0
	v_exp_f32_e32 v0, v0
	v_pk_fma_f32 v[78:79], v[70:71], v[4:5], v[66:67]
	v_add_f32_e32 v0, 1.0, v0
	v_rcp_f32_e32 v2, v0
	s_waitcnt vmcnt(12)
	v_lshlrev_b32_e32 v0, 16, v163
	v_mul_f32_e32 v0, 0xbfb8aa3b, v0
	v_exp_f32_e32 v0, v0
	v_mul_f32_e32 v69, v73, v78
	v_mul_f32_e32 v61, v69, v79
	v_add_f32_e32 v0, 1.0, v0
	v_rcp_f32_e32 v3, v0
	s_waitcnt vmcnt(11)
	v_lshlrev_b32_e32 v0, 16, v164
	v_mul_f32_e32 v0, 0xbfb8aa3b, v0
	v_exp_f32_e32 v0, v0
	v_pk_fma_f32 v[82:83], v[58:59], v[2:3], v[56:57]
	v_add_f32_e32 v0, 1.0, v0
	v_rcp_f32_e32 v4, v0
	s_waitcnt vmcnt(10)
	v_lshlrev_b32_e32 v0, 16, v165
	v_mul_f32_e32 v0, 0xbfb8aa3b, v0
	v_exp_f32_e32 v0, v0
	v_mul_f32_e32 v65, v61, v82
	v_mul_f32_e32 v55, v65, v83
	v_add_f32_e32 v0, 1.0, v0
	v_rcp_f32_e32 v5, v0
	s_waitcnt vmcnt(9)
	v_lshlrev_b32_e32 v0, 16, v167
	v_mul_f32_e32 v0, 0xbfb8aa3b, v0
	v_exp_f32_e32 v0, v0
	v_pk_fma_f32 v[80:81], v[70:71], v[4:5], v[66:67]
	v_add_f32_e32 v0, 1.0, v0
	v_rcp_f32_e32 v2, v0
	s_waitcnt vmcnt(8)
	v_lshlrev_b32_e32 v0, 16, v168
	v_mul_f32_e32 v0, 0xbfb8aa3b, v0
	v_exp_f32_e32 v0, v0
	v_mul_f32_e32 v53, v55, v80
	v_mul_f32_e32 v51, v53, v81
	v_add_f32_e32 v0, 1.0, v0
	v_rcp_f32_e32 v3, v0
	s_waitcnt vmcnt(7)
	v_lshlrev_b32_e32 v0, 16, v169
	v_mul_f32_e32 v0, 0xbfb8aa3b, v0
	v_exp_f32_e32 v0, v0
	v_pk_fma_f32 v[86:87], v[58:59], v[2:3], v[56:57]
	v_add_f32_e32 v0, 1.0, v0
	v_rcp_f32_e32 v4, v0
	s_waitcnt vmcnt(6)
	v_lshlrev_b32_e32 v0, 16, v170
	v_mul_f32_e32 v0, 0xbfb8aa3b, v0
	v_exp_f32_e32 v0, v0
	v_mul_f32_e32 v49, v51, v86
	v_mul_f32_e32 v47, v49, v87
	v_add_f32_e32 v0, 1.0, v0
	v_rcp_f32_e32 v5, v0
	s_waitcnt vmcnt(5)
	v_lshlrev_b32_e32 v0, 16, v171
	v_mul_f32_e32 v0, 0xbfb8aa3b, v0
	v_exp_f32_e32 v0, v0
	v_pk_fma_f32 v[84:85], v[70:71], v[4:5], v[66:67]
	v_add_f32_e32 v0, 1.0, v0
	v_rcp_f32_e32 v2, v0
	s_waitcnt vmcnt(4)
	v_lshlrev_b32_e32 v0, 16, v172
	v_mul_f32_e32 v0, 0xbfb8aa3b, v0
	v_exp_f32_e32 v0, v0
	v_mul_f32_e32 v45, v47, v84
	v_mul_f32_e32 v43, v45, v85
	v_add_f32_e32 v0, 1.0, v0
	v_rcp_f32_e32 v3, v0
	s_waitcnt vmcnt(3)
	v_lshlrev_b32_e32 v0, 16, v173
	v_mul_f32_e32 v0, 0xbfb8aa3b, v0
	v_exp_f32_e32 v0, v0
	v_pk_fma_f32 v[90:91], v[58:59], v[2:3], v[56:57]
	v_lshl_add_u32 v2, s10, 6, v166
	v_ashrrev_i32_e32 v3, 31, v2
	v_add_f32_e32 v0, 1.0, v0
	v_rcp_f32_e32 v4, v0
	s_waitcnt vmcnt(2)
	v_lshlrev_b32_e32 v0, 16, v174
	v_mul_f32_e32 v0, 0xbfb8aa3b, v0
	v_exp_f32_e32 v0, v0
	v_lshlrev_b64 v[2:3], 11, v[2:3]
	v_lshl_add_u64 v[146:147], v[62:63], 0, v[2:3]
	v_mul_f32_e32 v41, v43, v90
	v_add_f32_e32 v0, 1.0, v0
	v_rcp_f32_e32 v5, v0
	v_mul_f32_e32 v39, v41, v91
	s_cselect_b64 s[10:11], -1, 0
	s_and_b64 vcc, exec, s[10:11]
	v_pk_fma_f32 v[88:89], v[70:71], v[4:5], v[66:67]
	s_nop 0
	v_mul_f32_e32 v37, v39, v88
	v_mul_f32_e32 v35, v37, v89
	ds_write_b32 v94, v35
	s_waitcnt vmcnt(1)
	ds_write_b16 v132, v208 offset:62464
	ds_write_b16_d16_hi v133, v208 offset:62608
	ds_write_b16 v132, v209 offset:62752
	ds_write_b16_d16_hi v133, v209 offset:62896
	ds_write_b16 v132, v210 offset:63040
	ds_write_b16_d16_hi v133, v210 offset:63184
	ds_write_b16 v132, v211 offset:63328
	ds_write_b16_d16_hi v133, v211 offset:63472
	s_nop 0
	s_waitcnt vmcnt(0)
	ds_write_b16 v132, v212 offset:63616
	ds_write_b16_d16_hi v133, v212 offset:63760
	ds_write_b16 v132, v213 offset:63904
	ds_write_b16_d16_hi v133, v213 offset:64048
	ds_write_b16 v132, v214 offset:64192
	ds_write_b16_d16_hi v133, v214 offset:64336
	ds_write_b16 v132, v215 offset:64480
	ds_write_b16_d16_hi v133, v215 offset:64624
	s_cbranch_vccnz .LBB0_70
	s_and_b64 s[12:13], s[40:41], exec
	s_cselect_b32 s12, s49, s24
	s_lshl_b32 s12, s12, 6
	s_add_i32 s12, s12, s51
	v_add_u32_e32 v0, s12, v17
	v_lshl_or_b32 v0, v0, 11, v140
	v_add_u32_e32 v2, s12, v141
	v_add_u32_e32 v3, s12, v142
	v_add_u32_e32 v4, s12, v143
	v_add_u32_e32 v5, s12, v144
	v_add_u32_e32 v75, s12, v145
	v_add_u32_e32 v146, s12, v148
	v_add_u32_e32 v147, s12, v149
	v_lshl_or_b32 v2, v2, 11, v140
	v_lshl_or_b32 v3, v3, 11, v140
	v_lshl_or_b32 v4, v4, 11, v140
	v_lshl_or_b32 v5, v5, 11, v140
	v_lshl_or_b32 v75, v75, 11, v140
	v_lshl_or_b32 v146, v146, 11, v140
	v_lshl_or_b32 v147, v147, 11, v140
	global_load_ushort v156, v0, s[8:9]
	global_load_ushort v157, v2, s[8:9]
	global_load_ushort v159, v3, s[8:9]
	global_load_ushort v160, v4, s[8:9]
	global_load_ushort v162, v5, s[8:9]
	global_load_ushort v163, v75, s[8:9]
	global_load_ushort v164, v146, s[8:9]
	global_load_ushort v165, v147, s[8:9]
	v_add_u32_e32 v0, s12, v150
	v_lshl_or_b32 v0, v0, 11, v140
	v_add_u32_e32 v2, s12, v151
	v_add_u32_e32 v3, s12, v152
	v_add_u32_e32 v4, s12, v153
	v_add_u32_e32 v5, s12, v154
	v_add_u32_e32 v75, s12, v155
	v_add_u32_e32 v146, s12, v158
	v_add_u32_e32 v147, s12, v161
	v_lshl_or_b32 v2, v2, 11, v140
	v_lshl_or_b32 v3, v3, 11, v140
	v_lshl_or_b32 v4, v4, 11, v140
	v_lshl_or_b32 v5, v5, 11, v140
	v_lshl_or_b32 v75, v75, 11, v140
	v_lshl_or_b32 v146, v146, 11, v140
	v_lshl_or_b32 v147, v147, 11, v140
	global_load_ushort v167, v0, s[8:9]
	global_load_ushort v168, v2, s[8:9]
	global_load_ushort v169, v3, s[8:9]
	global_load_ushort v170, v4, s[8:9]
	global_load_ushort v171, v5, s[8:9]
	global_load_ushort v172, v75, s[8:9]
	global_load_ushort v173, v146, s[8:9]
	global_load_ushort v174, v147, s[8:9]

; __device__ __forceinline__ u32x4 pack8(const f32x4 a, const f32x4 b) { u32x4 w; w.x = cvt_pk_bf16(a[0], a[1]); w.y = cvt_pk_bf16(a[2], a[3]); w.z = cvt_pk_bf16(b[0], b[1]); w.w = cvt_pk_bf16(b[2], b[3]); return w; }
;     __device__ __forceinline__ void operator()(const f32x4 (&acc)[2][2][4][2], const Unit& u, int wr, int wc, int fr, int fq) const {
;         const int col0 = u.pn * 256 + wc * 32 + 8 * fq;
; #pragma unroll
;         for (int ai = 0; ai < 2; ++ai)
; #pragma unroll
;             for (int m = 0; m < 4; ++m) { const int row = u.pm * 256 + ai * 128 + wr * 64 + m * 16 + fr;
; #pragma unroll
;                 for (int bj = 0; bj < 2; ++bj) { const size_t off = (size_t)row * 1024 + col0 + bj * 128; const u32x4 hv = *(const u32x4*)(yb + off);
;                     f32x4 v0 = acc[ai][bj][m][0], v1 = acc[ai][bj][m][1];
;                     v0[0] *= __uint_as_float(hv.x << 16); v0[1] *= __uint_as_float(hv.x & 0xffff0000u); v0[2] *= __uint_as_float(hv.y << 16); v0[3] *= __uint_as_float(hv.y & 0xffff0000u);
;                     v1[0] *= __uint_as_float(hv.z << 16); v1[1] *= __uint_as_float(hv.z & 0xffff0000u); v1[2] *= __uint_as_float(hv.w << 16); v1[3] *= __uint_as_float(hv.w & 0xffff0000u);
;                     *(u32x4*)(outb + off) = pack8(v0, v1); }
;                 asm volatile("" ::: "memory"); }
.LBB0_112:
	v_lshl_add_u32 v142, s61, 8, v144
	v_lshl_or_b32 v140, s2, 8, v148
	v_ashrrev_i32_e32 v143, 31, v142
	v_ashrrev_i32_e32 v141, 31, v140
	v_mov_b32_e32 v240, v142
	v_ashrrev_i32_e32 v241, 31, v240
	v_lshlrev_b64 v[240:241], 10, v[240:241]
	v_lshl_add_u64 v[240:241], v[240:241], 0, v[140:141]
	v_lshlrev_b64 v[240:241], 1, v[240:241]
	v_lshl_add_u64 v[242:243], s[22:23], 0, v[240:241]
	global_load_dwordx4 v[156:159], v[242:243], off
	global_load_dwordx4 v[160:163], v[242:243], off offset:256
	v_add_u32_e32 v240, 0x10, v142
	v_ashrrev_i32_e32 v241, 31, v240
	v_lshlrev_b64 v[240:241], 10, v[240:241]
	v_lshl_add_u64 v[240:241], v[240:241], 0, v[140:141]
	v_lshlrev_b64 v[240:241], 1, v[240:241]
	v_lshl_add_u64 v[242:243], s[22:23], 0, v[240:241]
	global_load_dwordx4 v[164:167], v[242:243], off
	global_load_dwordx4 v[168:171], v[242:243], off offset:256
	v_add_u32_e32 v240, 0x20, v142
	v_ashrrev_i32_e32 v241, 31, v240
	v_lshlrev_b64 v[240:241], 10, v[240:241]
	v_lshl_add_u64 v[240:241], v[240:241], 0, v[140:141]
	v_lshlrev_b64 v[240:241], 1, v[240:241]
	v_lshl_add_u64 v[242:243], s[22:23], 0, v[240:241]
	global_load_dwordx4 v[172:175], v[242:243], off
	global_load_dwordx4 v[176:179], v[242:243], off offset:256
	v_add_u32_e32 v240, 0x30, v142
	v_ashrrev_i32_e32 v241, 31, v240
	v_lshlrev_b64 v[240:241], 10, v[240:241]
	v_lshl_add_u64 v[240:241], v[240:241], 0, v[140:141]
	v_lshlrev_b64 v[240:241], 1, v[240:241]
	v_lshl_add_u64 v[242:243], s[22:23], 0, v[240:241]
	global_load_dwordx4 v[180:183], v[242:243], off
	global_load_dwordx4 v[184:187], v[242:243], off offset:256
	v_add_u32_e32 v240, 0x80, v142
	v_ashrrev_i32_e32 v241, 31, v240
	v_lshlrev_b64 v[240:241], 10, v[240:241]
	v_lshl_add_u64 v[240:241], v[240:241], 0, v[140:141]
	v_lshlrev_b64 v[240:241], 1, v[240:241]
	v_lshl_add_u64 v[242:243], s[22:23], 0, v[240:241]
	global_load_dwordx4 v[188:191], v[242:243], off
	global_load_dwordx4 v[204:207], v[242:243], off offset:256
	v_add_u32_e32 v240, 0x90, v142
	v_ashrrev_i32_e32 v241, 31, v240
	v_lshlrev_b64 v[240:241], 10, v[240:241]
	v_lshl_add_u64 v[240:241], v[240:241], 0, v[140:141]
	v_lshlrev_b64 v[240:241], 1, v[240:241]
	v_lshl_add_u64 v[242:243], s[22:23], 0, v[240:241]
	global_load_dwordx4 v[208:211], v[242:243], off
	global_load_dwordx4 v[212:215], v[242:243], off offset:256
	v_add_u32_e32 v240, 0xa0, v142
	v_ashrrev_i32_e32 v241, 31, v240
	v_lshlrev_b64 v[240:241], 10, v[240:241]
	v_lshl_add_u64 v[240:241], v[240:241], 0, v[140:141]
	v_lshlrev_b64 v[240:241], 1, v[240:241]
	v_lshl_add_u64 v[242:243], s[22:23], 0, v[240:241]
	global_load_dwordx4 v[216:219], v[242:243], off
	global_load_dwordx4 v[228:231], v[242:243], off offset:256
	v_add_u32_e32 v240, 0xb0, v142
	v_ashrrev_i32_e32 v241, 31, v240
	v_lshlrev_b64 v[240:241], 10, v[240:241]
	v_lshl_add_u64 v[240:241], v[240:241], 0, v[140:141]
	v_lshlrev_b64 v[240:241], 1, v[240:241]
	v_lshl_add_u64 v[242:243], s[22:23], 0, v[240:241]
	global_load_dwordx4 v[232:235], v[242:243], off
	global_load_dwordx4 v[236:239], v[242:243], off offset:256
	v_lshlrev_b64 v[146:147], 10, v[142:143]
	v_lshl_add_u64 v[146:147], v[146:147], 0, v[140:141]
	v_lshlrev_b64 v[146:147], 1, v[146:147]
	v_lshl_add_u64 v[150:151], s[22:23], 0, v[146:147]
	s_waitcnt vmcnt(15)
	v_mov_b32_e32 v150, v156
	v_mov_b32_e32 v151, v157
	v_mov_b32_e32 v152, v158
	v_mov_b32_e32 v153, v159
	s_mov_b64 s[12:13], -1
	s_and_b64 vcc, exec, s[36:37]
	v_lshlrev_b32_e32 v154, 16, v150
	v_and_b32_e32 v155, 0xffff0000, v150
	v_lshlrev_b32_e32 v150, 16, v151
	v_and_b32_e32 v151, 0xffff0000, v151
	v_pk_mul_f32 v[128:129], v[128:129], v[150:151]
	v_lshlrev_b32_e32 v150, 16, v152
	v_and_b32_e32 v151, 0xffff0000, v152
	v_pk_mul_f32 v[150:151], v[122:123], v[150:151]
	v_lshlrev_b32_e32 v122, 16, v153
	v_and_b32_e32 v123, 0xffff0000, v153
	v_pk_mul_f32 v[126:127], v[126:127], v[154:155]
	v_pk_mul_f32 v[152:153], v[124:125], v[122:123]
	v_cvt_pk_bf16_f32 v122, v126, v127
	v_cvt_pk_bf16_f32 v123, v128, v129
	v_cvt_pk_bf16_f32 v124, v150, v151
	v_cvt_pk_bf16_f32 v125, v152, v153
	v_lshl_add_u64 v[126:127], s[16:17], 0, v[146:147]
	v_or_b32_e32 v146, 0x100, v146
	global_store_dwordx4 v[126:127], v[122:125], off
	s_nop 1
	v_lshl_add_u64 v[122:123], s[22:23], 0, v[146:147]
	s_waitcnt vmcnt(15)
	v_mov_b32_e32 v122, v160
	v_mov_b32_e32 v123, v161
	v_mov_b32_e32 v124, v162
	v_mov_b32_e32 v125, v163
	v_lshlrev_b32_e32 v126, 16, v122
	v_and_b32_e32 v127, 0xffff0000, v122
	v_lshlrev_b32_e32 v122, 16, v123
	v_and_b32_e32 v123, 0xffff0000, v123
	v_pk_mul_f32 v[120:121], v[120:121], v[122:123]
	v_lshlrev_b32_e32 v122, 16, v124
	v_and_b32_e32 v123, 0xffff0000, v124
	v_pk_mul_f32 v[122:123], v[114:115], v[122:123]
	v_lshlrev_b32_e32 v114, 16, v125
	v_and_b32_e32 v115, 0xffff0000, v125
	v_pk_mul_f32 v[118:119], v[118:119], v[126:127]
	v_pk_mul_f32 v[124:125], v[116:117], v[114:115]
	v_cvt_pk_bf16_f32 v114, v118, v119
	v_cvt_pk_bf16_f32 v115, v120, v121
	v_cvt_pk_bf16_f32 v116, v122, v123
	v_cvt_pk_bf16_f32 v117, v124, v125
	v_lshl_add_u64 v[118:119], s[16:17], 0, v[146:147]
	global_store_dwordx4 v[118:119], v[114:117], off
	s_nop 1
	v_or_b32_e32 v114, 16, v142
	v_ashrrev_i32_e32 v115, 31, v114
	v_lshlrev_b64 v[114:115], 10, v[114:115]
	v_lshl_add_u64 v[114:115], v[114:115], 0, v[140:141]
	v_lshlrev_b64 v[114:115], 1, v[114:115]
	v_lshl_add_u64 v[116:117], s[22:23], 0, v[114:115]
	s_waitcnt vmcnt(15)
; __device__ __forceinline__ u32x4 pack8(const f32x4 a, const f32x4 b) { u32x4 w; w.x = cvt_pk_bf16(a[0], a[1]); w.y = cvt_pk_bf16(a[2], a[3]); w.z = cvt_pk_bf16(b[0], b[1]); w.w = cvt_pk_bf16(b[2], b[3]); return w; }
;     __device__ __forceinline__ void operator()(const f32x4 (&acc)[2][2][4][2], const Unit& u, int wr, int wc, int fr, int fq) const {
;         const int col0 = u.pn * 256 + wc * 32 + 8 * fq;
; #pragma unroll
;         for (int ai = 0; ai < 2; ++ai)
; #pragma unroll
;             for (int m = 0; m < 4; ++m) { const int row = u.pm * 256 + ai * 128 + wr * 64 + m * 16 + fr;
; #pragma unroll
;                 for (int bj = 0; bj < 2; ++bj) { const size_t off = (size_t)row * 1024 + col0 + bj * 128; const u32x4 hv = *(const u32x4*)(yb + off);
;                     f32x4 v0 = acc[ai][bj][m][0], v1 = acc[ai][bj][m][1];
;                     v0[0] *= __uint_as_float(hv.x << 16); v0[1] *= __uint_as_float(hv.x & 0xffff0000u); v0[2] *= __uint_as_float(hv.y << 16); v0[3] *= __uint_as_float(hv.y & 0xffff0000u);
;                     v1[0] *= __uint_as_float(hv.z << 16); v1[1] *= __uint_as_float(hv.z & 0xffff0000u); v1[2] *= __uint_as_float(hv.w << 16); v1[3] *= __uint_as_float(hv.w & 0xffff0000u);
;                     *(u32x4*)(outb + off) = pack8(v0, v1); }
;                 asm volatile("" ::: "memory"); }
	v_mov_b32_e32 v116, v164
	v_mov_b32_e32 v117, v165
	v_mov_b32_e32 v118, v166
	v_mov_b32_e32 v119, v167
	v_lshlrev_b32_e32 v120, 16, v116
	v_and_b32_e32 v121, 0xffff0000, v116
	v_lshlrev_b32_e32 v116, 16, v117
	v_and_b32_e32 v117, 0xffff0000, v117
	v_pk_mul_f32 v[112:113], v[112:113], v[116:117]
	v_lshlrev_b32_e32 v116, 16, v118
	v_and_b32_e32 v117, 0xffff0000, v118
	v_pk_mul_f32 v[116:117], v[106:107], v[116:117]
	v_lshlrev_b32_e32 v106, 16, v119
	v_and_b32_e32 v107, 0xffff0000, v119
	v_pk_mul_f32 v[110:111], v[110:111], v[120:121]
	v_pk_mul_f32 v[118:119], v[108:109], v[106:107]
	v_cvt_pk_bf16_f32 v106, v110, v111
	v_cvt_pk_bf16_f32 v107, v112, v113
	v_cvt_pk_bf16_f32 v108, v116, v117
	v_cvt_pk_bf16_f32 v109, v118, v119
	v_lshl_add_u64 v[110:111], s[16:17], 0, v[114:115]
	v_or_b32_e32 v114, 0x100, v114
	global_store_dwordx4 v[110:111], v[106:109], off
	s_nop 1
	v_lshl_add_u64 v[106:107], s[22:23], 0, v[114:115]
	s_waitcnt vmcnt(15)
	v_mov_b32_e32 v106, v168
	v_mov_b32_e32 v107, v169
	v_mov_b32_e32 v108, v170
	v_mov_b32_e32 v109, v171
	v_lshlrev_b32_e32 v110, 16, v106
	v_and_b32_e32 v111, 0xffff0000, v106
	v_lshlrev_b32_e32 v106, 16, v107
	v_and_b32_e32 v107, 0xffff0000, v107
	v_pk_mul_f32 v[104:105], v[104:105], v[106:107]
	v_lshlrev_b32_e32 v106, 16, v108
	v_and_b32_e32 v107, 0xffff0000, v108
	v_pk_mul_f32 v[106:107], v[98:99], v[106:107]
	v_lshlrev_b32_e32 v98, 16, v109
	v_and_b32_e32 v99, 0xffff0000, v109
	v_pk_mul_f32 v[102:103], v[102:103], v[110:111]
	v_pk_mul_f32 v[108:109], v[100:101], v[98:99]
	v_cvt_pk_bf16_f32 v98, v102, v103
	v_cvt_pk_bf16_f32 v99, v104, v105
	v_cvt_pk_bf16_f32 v100, v106, v107
	v_cvt_pk_bf16_f32 v101, v108, v109
	v_lshl_add_u64 v[102:103], s[16:17], 0, v[114:115]
	global_store_dwordx4 v[102:103], v[98:101], off
	s_nop 1
	v_or_b32_e32 v98, 32, v142
	v_ashrrev_i32_e32 v99, 31, v98
	v_lshlrev_b64 v[98:99], 10, v[98:99]
	v_lshl_add_u64 v[98:99], v[98:99], 0, v[140:141]
	v_lshlrev_b64 v[98:99], 1, v[98:99]
	v_lshl_add_u64 v[100:101], s[22:23], 0, v[98:99]
	s_waitcnt vmcnt(15)
	v_mov_b32_e32 v100, v172
	v_mov_b32_e32 v101, v173
	v_mov_b32_e32 v102, v174
	v_mov_b32_e32 v103, v175
	v_lshlrev_b32_e32 v104, 16, v100
	v_and_b32_e32 v105, 0xffff0000, v100
	v_lshlrev_b32_e32 v100, 16, v101
	v_and_b32_e32 v101, 0xffff0000, v101
	v_pk_mul_f32 v[96:97], v[96:97], v[100:101]
	v_lshlrev_b32_e32 v100, 16, v102
	v_and_b32_e32 v101, 0xffff0000, v102
	v_pk_mul_f32 v[100:101], v[90:91], v[100:101]
	v_lshlrev_b32_e32 v90, 16, v103
	v_and_b32_e32 v91, 0xffff0000, v103
	v_pk_mul_f32 v[94:95], v[94:95], v[104:105]
	v_pk_mul_f32 v[102:103], v[92:93], v[90:91]
	v_cvt_pk_bf16_f32 v90, v94, v95
	v_cvt_pk_bf16_f32 v91, v96, v97
	v_cvt_pk_bf16_f32 v92, v100, v101
	v_cvt_pk_bf16_f32 v93, v102, v103
	v_lshl_add_u64 v[94:95], s[16:17], 0, v[98:99]
	v_or_b32_e32 v98, 0x100, v98
	global_store_dwordx4 v[94:95], v[90:93], off
	s_nop 1
	v_lshl_add_u64 v[90:91], s[22:23], 0, v[98:99]
	s_waitcnt vmcnt(15)
	v_mov_b32_e32 v90, v176
	v_mov_b32_e32 v91, v177
	v_mov_b32_e32 v92, v178
	v_mov_b32_e32 v93, v179
	v_lshlrev_b32_e32 v94, 16, v90
	v_and_b32_e32 v95, 0xffff0000, v90
	v_lshlrev_b32_e32 v90, 16, v91
	v_and_b32_e32 v91, 0xffff0000, v91
	v_pk_mul_f32 v[88:89], v[88:89], v[90:91]
	v_lshlrev_b32_e32 v90, 16, v92
	v_and_b32_e32 v91, 0xffff0000, v92
	v_pk_mul_f32 v[90:91], v[82:83], v[90:91]
	v_lshlrev_b32_e32 v82, 16, v93
	v_and_b32_e32 v83, 0xffff0000, v93
	v_pk_mul_f32 v[86:87], v[86:87], v[94:95]
	v_pk_mul_f32 v[92:93], v[84:85], v[82:83]
	v_cvt_pk_bf16_f32 v82, v86, v87
	v_cvt_pk_bf16_f32 v83, v88, v89
	v_cvt_pk_bf16_f32 v84, v90, v91
	v_cvt_pk_bf16_f32 v85, v92, v93
	v_lshl_add_u64 v[86:87], s[16:17], 0, v[98:99]
	global_store_dwordx4 v[86:87], v[82:85], off
	s_nop 1
	v_or_b32_e32 v82, 48, v142
	v_ashrrev_i32_e32 v83, 31, v82
	v_lshlrev_b64 v[82:83], 10, v[82:83]
	v_lshl_add_u64 v[82:83], v[82:83], 0, v[140:141]
	v_lshlrev_b64 v[82:83], 1, v[82:83]
	v_lshl_add_u64 v[84:85], s[22:23], 0, v[82:83]
	s_waitcnt vmcnt(15)
	v_mov_b32_e32 v84, v180
	v_mov_b32_e32 v85, v181
	v_mov_b32_e32 v86, v182
	v_mov_b32_e32 v87, v183
	v_lshlrev_b32_e32 v88, 16, v84
	v_and_b32_e32 v89, 0xffff0000, v84
	v_lshlrev_b32_e32 v84, 16, v85
	v_and_b32_e32 v85, 0xffff0000, v85
	v_pk_mul_f32 v[80:81], v[80:81], v[84:85]
	v_lshlrev_b32_e32 v84, 16, v86
	v_and_b32_e32 v85, 0xffff0000, v86
	v_pk_mul_f32 v[84:85], v[74:75], v[84:85]
	v_lshlrev_b32_e32 v74, 16, v87
	v_and_b32_e32 v75, 0xffff0000, v87
	v_pk_mul_f32 v[78:79], v[78:79], v[88:89]
	v_pk_mul_f32 v[86:87], v[76:77], v[74:75]
	v_cvt_pk_bf16_f32 v74, v78, v79
	v_cvt_pk_bf16_f32 v75, v80, v81
	v_cvt_pk_bf16_f32 v76, v84, v85
	v_cvt_pk_bf16_f32 v77, v86, v87
	v_lshl_add_u64 v[78:79], s[16:17], 0, v[82:83]
	v_or_b32_e32 v82, 0x100, v82
	global_store_dwordx4 v[78:79], v[74:77], off
	s_nop 1
	v_lshl_add_u64 v[74:75], s[22:23], 0, v[82:83]
	s_waitcnt vmcnt(15)
	v_mov_b32_e32 v74, v184
	v_mov_b32_e32 v75, v185
	v_mov_b32_e32 v76, v186
	v_mov_b32_e32 v77, v187
	v_lshlrev_b32_e32 v78, 16, v74
	v_and_b32_e32 v79, 0xffff0000, v74
	v_lshlrev_b32_e32 v74, 16, v75
	v_and_b32_e32 v75, 0xffff0000, v75
	v_pk_mul_f32 v[72:73], v[72:73], v[74:75]
	v_lshlrev_b32_e32 v74, 16, v76
	v_and_b32_e32 v75, 0xffff0000, v76
	v_pk_mul_f32 v[74:75], v[66:67], v[74:75]
	v_lshlrev_b32_e32 v66, 16, v77
	v_and_b32_e32 v67, 0xffff0000, v77
	v_pk_mul_f32 v[70:71], v[70:71], v[78:79]
	v_pk_mul_f32 v[76:77], v[68:69], v[66:67]
	v_cvt_pk_bf16_f32 v66, v70, v71
	v_cvt_pk_bf16_f32 v67, v72, v73
	v_cvt_pk_bf16_f32 v68, v74, v75
	v_cvt_pk_bf16_f32 v69, v76, v77
	v_lshl_add_u64 v[70:71], s[16:17], 0, v[82:83]
	global_store_dwordx4 v[70:71], v[66:69], off
	s_nop 1
	v_add_u32_e32 v66, 0x80, v142
	v_ashrrev_i32_e32 v67, 31, v66
	v_lshlrev_b64 v[66:67], 10, v[66:67]
	v_lshl_add_u64 v[66:67], v[66:67], 0, v[140:141]
	v_lshlrev_b64 v[66:67], 1, v[66:67]
	v_lshl_add_u64 v[68:69], s[22:23], 0, v[66:67]
	s_waitcnt vmcnt(15)
; __device__ __forceinline__ u32x4 pack8(const f32x4 a, const f32x4 b) { u32x4 w; w.x = cvt_pk_bf16(a[0], a[1]); w.y = cvt_pk_bf16(a[2], a[3]); w.z = cvt_pk_bf16(b[0], b[1]); w.w = cvt_pk_bf16(b[2], b[3]); return w; }
;     __device__ __forceinline__ void operator()(const f32x4 (&acc)[2][2][4][2], const Unit& u, int wr, int wc, int fr, int fq) const {
;         const int col0 = u.pn * 256 + wc * 32 + 8 * fq;
; #pragma unroll
;         for (int ai = 0; ai < 2; ++ai)
; #pragma unroll
;             for (int m = 0; m < 4; ++m) { const int row = u.pm * 256 + ai * 128 + wr * 64 + m * 16 + fr;
; #pragma unroll
;                 for (int bj = 0; bj < 2; ++bj) { const size_t off = (size_t)row * 1024 + col0 + bj * 128; const u32x4 hv = *(const u32x4*)(yb + off);
;                     f32x4 v0 = acc[ai][bj][m][0], v1 = acc[ai][bj][m][1];
;                     v0[0] *= __uint_as_float(hv.x << 16); v0[1] *= __uint_as_float(hv.x & 0xffff0000u); v0[2] *= __uint_as_float(hv.y << 16); v0[3] *= __uint_as_float(hv.y & 0xffff0000u);
;                     v1[0] *= __uint_as_float(hv.z << 16); v1[1] *= __uint_as_float(hv.z & 0xffff0000u); v1[2] *= __uint_as_float(hv.w << 16); v1[3] *= __uint_as_float(hv.w & 0xffff0000u);
;                     *(u32x4*)(outb + off) = pack8(v0, v1); }
;                 asm volatile("" ::: "memory"); }
	v_mov_b32_e32 v68, v188
	v_mov_b32_e32 v69, v189
	v_mov_b32_e32 v70, v190
	v_mov_b32_e32 v71, v191
	v_lshlrev_b32_e32 v72, 16, v68
	v_and_b32_e32 v73, 0xffff0000, v68
	v_lshlrev_b32_e32 v68, 16, v69
	v_and_b32_e32 v69, 0xffff0000, v69
	v_pk_mul_f32 v[64:65], v[64:65], v[68:69]
	v_lshlrev_b32_e32 v68, 16, v70
	v_and_b32_e32 v69, 0xffff0000, v70
	v_pk_mul_f32 v[68:69], v[58:59], v[68:69]
	v_lshlrev_b32_e32 v58, 16, v71
	v_and_b32_e32 v59, 0xffff0000, v71
	v_pk_mul_f32 v[62:63], v[62:63], v[72:73]
	v_pk_mul_f32 v[70:71], v[60:61], v[58:59]
	v_cvt_pk_bf16_f32 v58, v62, v63
	v_cvt_pk_bf16_f32 v59, v64, v65
	v_cvt_pk_bf16_f32 v60, v68, v69
	v_cvt_pk_bf16_f32 v61, v70, v71
	v_lshl_add_u64 v[62:63], s[16:17], 0, v[66:67]
	v_or_b32_e32 v66, 0x100, v66
	global_store_dwordx4 v[62:63], v[58:61], off
	s_nop 1
	v_lshl_add_u64 v[58:59], s[22:23], 0, v[66:67]
	s_waitcnt vmcnt(15)
	v_mov_b32_e32 v58, v204
	v_mov_b32_e32 v59, v205
	v_mov_b32_e32 v60, v206
	v_mov_b32_e32 v61, v207
	v_lshlrev_b32_e32 v62, 16, v58
	v_and_b32_e32 v63, 0xffff0000, v58
	v_lshlrev_b32_e32 v58, 16, v59
	v_and_b32_e32 v59, 0xffff0000, v59
	v_pk_mul_f32 v[56:57], v[56:57], v[58:59]
	v_lshlrev_b32_e32 v58, 16, v60
	v_and_b32_e32 v59, 0xffff0000, v60
	v_pk_mul_f32 v[58:59], v[50:51], v[58:59]
	v_lshlrev_b32_e32 v50, 16, v61
	v_and_b32_e32 v51, 0xffff0000, v61
	v_pk_mul_f32 v[54:55], v[54:55], v[62:63]
	v_pk_mul_f32 v[60:61], v[52:53], v[50:51]
	v_cvt_pk_bf16_f32 v50, v54, v55
	v_cvt_pk_bf16_f32 v51, v56, v57
	v_cvt_pk_bf16_f32 v52, v58, v59
	v_cvt_pk_bf16_f32 v53, v60, v61
	v_lshl_add_u64 v[54:55], s[16:17], 0, v[66:67]
	global_store_dwordx4 v[54:55], v[50:53], off
	s_nop 1
	v_add_u32_e32 v50, 0x90, v142
	v_ashrrev_i32_e32 v51, 31, v50
	v_lshlrev_b64 v[50:51], 10, v[50:51]
	v_lshl_add_u64 v[50:51], v[50:51], 0, v[140:141]
	v_lshlrev_b64 v[50:51], 1, v[50:51]
	v_lshl_add_u64 v[52:53], s[22:23], 0, v[50:51]
	s_waitcnt vmcnt(15)
	v_mov_b32_e32 v52, v208
	v_mov_b32_e32 v53, v209
	v_mov_b32_e32 v54, v210
	v_mov_b32_e32 v55, v211
	v_lshlrev_b32_e32 v56, 16, v52
	v_and_b32_e32 v57, 0xffff0000, v52
	v_lshlrev_b32_e32 v52, 16, v53
	v_and_b32_e32 v53, 0xffff0000, v53
	v_pk_mul_f32 v[48:49], v[48:49], v[52:53]
	v_lshlrev_b32_e32 v52, 16, v54
	v_and_b32_e32 v53, 0xffff0000, v54
	v_pk_mul_f32 v[52:53], v[42:43], v[52:53]
	v_lshlrev_b32_e32 v42, 16, v55
	v_and_b32_e32 v43, 0xffff0000, v55
	v_pk_mul_f32 v[46:47], v[46:47], v[56:57]
	v_pk_mul_f32 v[54:55], v[44:45], v[42:43]
	v_cvt_pk_bf16_f32 v42, v46, v47
	v_cvt_pk_bf16_f32 v43, v48, v49
	v_cvt_pk_bf16_f32 v44, v52, v53
	v_cvt_pk_bf16_f32 v45, v54, v55
	v_lshl_add_u64 v[46:47], s[16:17], 0, v[50:51]
	v_or_b32_e32 v50, 0x100, v50
	global_store_dwordx4 v[46:47], v[42:45], off
	s_nop 1
	v_lshl_add_u64 v[42:43], s[22:23], 0, v[50:51]
	s_waitcnt vmcnt(15)
	v_mov_b32_e32 v42, v212
	v_mov_b32_e32 v43, v213
	v_mov_b32_e32 v44, v214
	v_mov_b32_e32 v45, v215
	v_lshlrev_b32_e32 v46, 16, v42
	v_and_b32_e32 v47, 0xffff0000, v42
	v_lshlrev_b32_e32 v42, 16, v43
	v_and_b32_e32 v43, 0xffff0000, v43
	v_pk_mul_f32 v[40:41], v[40:41], v[42:43]
	v_lshlrev_b32_e32 v42, 16, v44
	v_and_b32_e32 v43, 0xffff0000, v44
	v_pk_mul_f32 v[42:43], v[34:35], v[42:43]
	v_lshlrev_b32_e32 v34, 16, v45
	v_and_b32_e32 v35, 0xffff0000, v45
	v_pk_mul_f32 v[38:39], v[38:39], v[46:47]
	v_pk_mul_f32 v[44:45], v[36:37], v[34:35]
	v_cvt_pk_bf16_f32 v34, v38, v39
	v_cvt_pk_bf16_f32 v35, v40, v41
	v_cvt_pk_bf16_f32 v36, v42, v43
	v_cvt_pk_bf16_f32 v37, v44, v45
	v_lshl_add_u64 v[38:39], s[16:17], 0, v[50:51]
	global_store_dwordx4 v[38:39], v[34:37], off
	s_nop 1
	v_add_u32_e32 v34, 0xa0, v142
	v_ashrrev_i32_e32 v35, 31, v34
	v_lshlrev_b64 v[34:35], 10, v[34:35]
	v_lshl_add_u64 v[34:35], v[34:35], 0, v[140:141]
	v_lshlrev_b64 v[34:35], 1, v[34:35]
	v_lshl_add_u64 v[36:37], s[22:23], 0, v[34:35]
	s_waitcnt vmcnt(15)
; __device__ __forceinline__ u32x4 pack8(const f32x4 a, const f32x4 b) { u32x4 w; w.x = cvt_pk_bf16(a[0], a[1]); w.y = cvt_pk_bf16(a[2], a[3]); w.z = cvt_pk_bf16(b[0], b[1]); w.w = cvt_pk_bf16(b[2], b[3]); return w; }
;     __device__ __forceinline__ void operator()(const f32x4 (&acc)[2][2][4][2], const Unit& u, int wr, int wc, int fr, int fq) const {
;         const int col0 = u.pn * 256 + wc * 32 + 8 * fq;
; #pragma unroll
;         for (int ai = 0; ai < 2; ++ai)
; #pragma unroll
;             for (int m = 0; m < 4; ++m) { const int row = u.pm * 256 + ai * 128 + wr * 64 + m * 16 + fr;
; #pragma unroll
;                 for (int bj = 0; bj < 2; ++bj) { const size_t off = (size_t)row * 1024 + col0 + bj * 128; const u32x4 hv = *(const u32x4*)(yb + off);
;                     f32x4 v0 = acc[ai][bj][m][0], v1 = acc[ai][bj][m][1];
;                     v0[0] *= __uint_as_float(hv.x << 16); v0[1] *= __uint_as_float(hv.x & 0xffff0000u); v0[2] *= __uint_as_float(hv.y << 16); v0[3] *= __uint_as_float(hv.y & 0xffff0000u);
;                     v1[0] *= __uint_as_float(hv.z << 16); v1[1] *= __uint_as_float(hv.z & 0xffff0000u); v1[2] *= __uint_as_float(hv.w << 16); v1[3] *= __uint_as_float(hv.w & 0xffff0000u);
;                     *(u32x4*)(outb + off) = pack8(v0, v1); }
;                 asm volatile("" ::: "memory"); }
	v_mov_b32_e32 v36, v216
	v_mov_b32_e32 v37, v217
	v_mov_b32_e32 v38, v218
	v_mov_b32_e32 v39, v219
	v_lshlrev_b32_e32 v40, 16, v36
	v_and_b32_e32 v41, 0xffff0000, v36
	v_lshlrev_b32_e32 v36, 16, v37
	v_and_b32_e32 v37, 0xffff0000, v37
	v_pk_mul_f32 v[32:33], v[32:33], v[36:37]
	v_lshlrev_b32_e32 v36, 16, v38
	v_and_b32_e32 v37, 0xffff0000, v38
	v_pk_mul_f32 v[36:37], v[26:27], v[36:37]
	v_lshlrev_b32_e32 v26, 16, v39
	v_and_b32_e32 v27, 0xffff0000, v39
	v_pk_mul_f32 v[30:31], v[30:31], v[40:41]
	v_pk_mul_f32 v[38:39], v[28:29], v[26:27]
	v_cvt_pk_bf16_f32 v26, v30, v31
	v_cvt_pk_bf16_f32 v27, v32, v33
	v_cvt_pk_bf16_f32 v28, v36, v37
	v_cvt_pk_bf16_f32 v29, v38, v39
	v_lshl_add_u64 v[30:31], s[16:17], 0, v[34:35]
	v_or_b32_e32 v34, 0x100, v34
	global_store_dwordx4 v[30:31], v[26:29], off
	s_nop 1
	v_lshl_add_u64 v[26:27], s[22:23], 0, v[34:35]
	s_waitcnt vmcnt(15)
	v_mov_b32_e32 v26, v228
	v_mov_b32_e32 v27, v229
	v_mov_b32_e32 v28, v230
	v_mov_b32_e32 v29, v231
	v_lshlrev_b32_e32 v30, 16, v26
	v_and_b32_e32 v31, 0xffff0000, v26
	v_lshlrev_b32_e32 v26, 16, v27
	v_and_b32_e32 v27, 0xffff0000, v27
	v_pk_mul_f32 v[24:25], v[24:25], v[26:27]
	v_lshlrev_b32_e32 v26, 16, v28
	v_and_b32_e32 v27, 0xffff0000, v28
	v_pk_mul_f32 v[26:27], v[18:19], v[26:27]
	v_lshlrev_b32_e32 v18, 16, v29
	v_and_b32_e32 v19, 0xffff0000, v29
	v_pk_mul_f32 v[22:23], v[22:23], v[30:31]
	v_pk_mul_f32 v[28:29], v[20:21], v[18:19]
	v_cvt_pk_bf16_f32 v18, v22, v23
	v_cvt_pk_bf16_f32 v19, v24, v25
	v_cvt_pk_bf16_f32 v20, v26, v27
	v_cvt_pk_bf16_f32 v21, v28, v29
	v_lshl_add_u64 v[22:23], s[16:17], 0, v[34:35]
	global_store_dwordx4 v[22:23], v[18:21], off
	s_nop 1
	v_add_u32_e32 v18, 0xb0, v142
	v_ashrrev_i32_e32 v19, 31, v18
	v_lshlrev_b64 v[18:19], 10, v[18:19]
	v_lshl_add_u64 v[18:19], v[18:19], 0, v[140:141]
	v_lshlrev_b64 v[18:19], 1, v[18:19]
	v_lshl_add_u64 v[20:21], s[22:23], 0, v[18:19]
	s_waitcnt vmcnt(15)
	v_mov_b32_e32 v20, v232
	v_mov_b32_e32 v21, v233
	v_mov_b32_e32 v22, v234
	v_mov_b32_e32 v23, v235
	v_lshlrev_b32_e32 v24, 16, v20
	v_and_b32_e32 v25, 0xffff0000, v20
	v_lshlrev_b32_e32 v20, 16, v21
	v_and_b32_e32 v21, 0xffff0000, v21
	v_pk_mul_f32 v[16:17], v[16:17], v[20:21]
	v_lshlrev_b32_e32 v20, 16, v22
	v_and_b32_e32 v21, 0xffff0000, v22
	v_pk_mul_f32 v[20:21], v[10:11], v[20:21]
	v_lshlrev_b32_e32 v10, 16, v23
	v_and_b32_e32 v11, 0xffff0000, v23
	v_pk_mul_f32 v[14:15], v[14:15], v[24:25]
	v_pk_mul_f32 v[22:23], v[12:13], v[10:11]
	v_cvt_pk_bf16_f32 v10, v14, v15
	v_cvt_pk_bf16_f32 v11, v16, v17
	v_cvt_pk_bf16_f32 v12, v20, v21
	v_cvt_pk_bf16_f32 v13, v22, v23
	v_lshl_add_u64 v[14:15], s[16:17], 0, v[18:19]
	v_or_b32_e32 v18, 0x100, v18
	global_store_dwordx4 v[14:15], v[10:13], off
	s_nop 1
	v_lshl_add_u64 v[10:11], s[22:23], 0, v[18:19]
	s_waitcnt vmcnt(15)
	v_mov_b32_e32 v10, v236
	v_mov_b32_e32 v11, v237
	v_mov_b32_e32 v12, v238
	v_mov_b32_e32 v13, v239
	v_lshlrev_b32_e32 v14, 16, v10
	v_and_b32_e32 v15, 0xffff0000, v10
	v_lshlrev_b32_e32 v10, 16, v11
	v_and_b32_e32 v11, 0xffff0000, v11
	v_pk_mul_f32 v[8:9], v[8:9], v[10:11]
	v_lshlrev_b32_e32 v10, 16, v12
	v_and_b32_e32 v11, 0xffff0000, v12
	v_pk_mul_f32 v[10:11], v[2:3], v[10:11]
	v_lshlrev_b32_e32 v2, 16, v13
	v_and_b32_e32 v3, 0xffff0000, v13
	v_pk_mul_f32 v[6:7], v[6:7], v[14:15]
	v_pk_mul_f32 v[12:13], v[4:5], v[2:3]
	v_cvt_pk_bf16_f32 v2, v6, v7
	v_cvt_pk_bf16_f32 v3, v8, v9
	v_cvt_pk_bf16_f32 v4, v10, v11
	v_cvt_pk_bf16_f32 v5, v12, v13
	v_lshl_add_u64 v[6:7], s[16:17], 0, v[18:19]
	global_store_dwordx4 v[6:7], v[2:5], off
	s_cbranch_vccnz .LBB0_95
	s_andn2_b64 vcc, exec, s[10:11]
	s_cbranch_vccnz .LBB0_94
	s_barrier
	s_branch .LBB0_94

; __device__ __forceinline__ unsigned f2bf(float f) { return pk2(f, 0.f) & 0xffffu; }
; template <bool PA> ...
;     ...
;         for (int i = tid; i < 4096; i += 512) { const int l = i >> 6, cc = i & 63; w2T[cc * 72 + l] = (bf16)f2bf(w2[(size_t)l * 1024 + head * 64 + cc]); a2T[cc * 72 + l] = (bf16)f2bf(a2[(size_t)l * 1024 + head * 64 + cc]); }
.LBB0_145:
	v_ashrrev_i32_e32 v4, 6, v2
	v_ashrrev_i32_e32 v5, 31, v4
	v_lshlrev_b64 v[6:7], 12, v[4:5]
	v_lshl_or_b32 v6, v0, 2, v6
	v_add_u32_e32 v4, v4, v116
	v_lshl_add_u32 v8, v4, 1, 0
	v_add_u32_e32 v222, 0x1d400, v8
	v_add_u32_e32 v223, 0x1f800, v8
	v_lshl_add_u64 v[220:221], s[20:21], 0, v[6:7]
	global_load_dword v204, v[220:221], off
	v_lshl_add_u64 v[220:221], s[92:93], 0, v[6:7]
	global_load_dword v205, v[220:221], off
	s_add_u32 s20, s20, 0x8000
	s_addc_u32 s21, s21, 0
	s_add_u32 s92, s92, 0x8000
	s_addc_u32 s93, s93, 0
	v_lshl_add_u64 v[220:221], s[20:21], 0, v[6:7]
	global_load_dword v206, v[220:221], off
	v_lshl_add_u64 v[220:221], s[92:93], 0, v[6:7]
	global_load_dword v207, v[220:221], off
	s_add_u32 s20, s20, 0x8000
	s_addc_u32 s21, s21, 0
	s_add_u32 s92, s92, 0x8000
	s_addc_u32 s93, s93, 0
	v_lshl_add_u64 v[220:221], s[20:21], 0, v[6:7]
	global_load_dword v208, v[220:221], off
	v_lshl_add_u64 v[220:221], s[92:93], 0, v[6:7]
	global_load_dword v209, v[220:221], off
	s_add_u32 s20, s20, 0x8000
	s_addc_u32 s21, s21, 0
	s_add_u32 s92, s92, 0x8000
	s_addc_u32 s93, s93, 0
	v_lshl_add_u64 v[220:221], s[20:21], 0, v[6:7]
	global_load_dword v210, v[220:221], off
	v_lshl_add_u64 v[220:221], s[92:93], 0, v[6:7]
	global_load_dword v211, v[220:221], off
	s_add_u32 s20, s20, 0x8000
	s_addc_u32 s21, s21, 0
	s_add_u32 s92, s92, 0x8000
	s_addc_u32 s93, s93, 0
	v_lshl_add_u64 v[220:221], s[20:21], 0, v[6:7]
	global_load_dword v212, v[220:221], off
	v_lshl_add_u64 v[220:221], s[92:93], 0, v[6:7]
	global_load_dword v213, v[220:221], off
	s_add_u32 s20, s20, 0x8000
	s_addc_u32 s21, s21, 0
	s_add_u32 s92, s92, 0x8000
	s_addc_u32 s93, s93, 0
	v_lshl_add_u64 v[220:221], s[20:21], 0, v[6:7]
	global_load_dword v214, v[220:221], off
	v_lshl_add_u64 v[220:221], s[92:93], 0, v[6:7]
	global_load_dword v215, v[220:221], off
	s_add_u32 s20, s20, 0x8000
	s_addc_u32 s21, s21, 0
	s_add_u32 s92, s92, 0x8000
	s_addc_u32 s93, s93, 0
	v_lshl_add_u64 v[220:221], s[20:21], 0, v[6:7]
	global_load_dword v216, v[220:221], off
	v_lshl_add_u64 v[220:221], s[92:93], 0, v[6:7]
	global_load_dword v217, v[220:221], off
	s_add_u32 s20, s20, 0x8000
	s_addc_u32 s21, s21, 0
	s_add_u32 s92, s92, 0x8000
	s_addc_u32 s93, s93, 0
	v_lshl_add_u64 v[220:221], s[20:21], 0, v[6:7]
	global_load_dword v218, v[220:221], off
	v_lshl_add_u64 v[220:221], s[92:93], 0, v[6:7]
	global_load_dword v219, v[220:221], off
	s_sub_u32 s20, s20, 0x38000
	s_subb_u32 s21, s21, 0
	s_sub_u32 s92, s92, 0x38000
	s_subb_u32 s93, s93, 0
	s_waitcnt vmcnt(15)
	v_cvt_pk_bf16_f32 v3, v204, s0
	ds_write_b16 v222, v3 offset:0
	s_waitcnt vmcnt(14)
	v_cvt_pk_bf16_f32 v9, v205, s0
	ds_write_b16 v223, v9 offset:0
	s_waitcnt vmcnt(13)
	v_cvt_pk_bf16_f32 v3, v206, s0
	ds_write_b16 v222, v3 offset:16
	s_waitcnt vmcnt(12)
	v_cvt_pk_bf16_f32 v9, v207, s0
	ds_write_b16 v223, v9 offset:16
	s_waitcnt vmcnt(11)
	v_cvt_pk_bf16_f32 v3, v208, s0
	ds_write_b16 v222, v3 offset:32
	s_waitcnt vmcnt(10)
	v_cvt_pk_bf16_f32 v9, v209, s0
	ds_write_b16 v223, v9 offset:32
	s_waitcnt vmcnt(9)
	v_cvt_pk_bf16_f32 v3, v210, s0
	ds_write_b16 v222, v3 offset:48
	s_waitcnt vmcnt(8)
	v_cvt_pk_bf16_f32 v9, v211, s0
	ds_write_b16 v223, v9 offset:48
	s_waitcnt vmcnt(7)
	v_cvt_pk_bf16_f32 v3, v212, s0
	ds_write_b16 v222, v3 offset:64
	s_waitcnt vmcnt(6)
	v_cvt_pk_bf16_f32 v9, v213, s0
	ds_write_b16 v223, v9 offset:64
	s_waitcnt vmcnt(5)
	v_cvt_pk_bf16_f32 v3, v214, s0
	ds_write_b16 v222, v3 offset:80
	s_waitcnt vmcnt(4)
	v_cvt_pk_bf16_f32 v9, v215, s0
	ds_write_b16 v223, v9 offset:80
	s_waitcnt vmcnt(3)
	v_cvt_pk_bf16_f32 v3, v216, s0
	ds_write_b16 v222, v3 offset:96
	s_waitcnt vmcnt(2)
	v_cvt_pk_bf16_f32 v9, v217, s0
	ds_write_b16 v223, v9 offset:96
	s_waitcnt vmcnt(1)
	v_cvt_pk_bf16_f32 v3, v218, s0
	ds_write_b16 v222, v3 offset:112
	s_waitcnt vmcnt(0)
	v_cvt_pk_bf16_f32 v9, v219, s0
	ds_write_b16 v223, v9 offset:112

; __device__ __forceinline__ unsigned f2bf(float f) { return pk2(f, 0.f) & 0xffffu; }
; template <bool PA> ...
;     ...
;         for (int i = tid; i < 4096; i += 512) { const int l = i >> 6, cc = i & 63; w2T[cc * 72 + l] = (bf16)f2bf(w2[(size_t)l * 1024 + head * 64 + cc]); a2T[cc * 72 + l] = (bf16)f2bf(a2[(size_t)l * 1024 + head * 64 + cc]); }
.LBB0_210:
	v_ashrrev_i32_e32 v4, 6, v2
	v_ashrrev_i32_e32 v5, 31, v4
	v_lshlrev_b64 v[6:7], 12, v[4:5]
	v_lshl_or_b32 v6, v0, 2, v6
	v_add_u32_e32 v4, v4, v135
	v_lshl_add_u32 v8, v4, 1, 0
	v_add_u32_e32 v222, 0x1d400, v8
	v_add_u32_e32 v223, 0x1f800, v8
	v_lshl_add_u64 v[220:221], s[20:21], 0, v[6:7]
	global_load_dword v204, v[220:221], off
	v_lshl_add_u64 v[220:221], s[76:77], 0, v[6:7]
	global_load_dword v205, v[220:221], off
	s_add_u32 s20, s20, 0x8000
	s_addc_u32 s21, s21, 0
	s_add_u32 s76, s76, 0x8000
	s_addc_u32 s77, s77, 0
	v_lshl_add_u64 v[220:221], s[20:21], 0, v[6:7]
	global_load_dword v206, v[220:221], off
	v_lshl_add_u64 v[220:221], s[76:77], 0, v[6:7]
	global_load_dword v207, v[220:221], off
	s_add_u32 s20, s20, 0x8000
	s_addc_u32 s21, s21, 0
	s_add_u32 s76, s76, 0x8000
	s_addc_u32 s77, s77, 0
	v_lshl_add_u64 v[220:221], s[20:21], 0, v[6:7]
	global_load_dword v208, v[220:221], off
	v_lshl_add_u64 v[220:221], s[76:77], 0, v[6:7]
	global_load_dword v209, v[220:221], off
	s_add_u32 s20, s20, 0x8000
	s_addc_u32 s21, s21, 0
	s_add_u32 s76, s76, 0x8000
	s_addc_u32 s77, s77, 0
	v_lshl_add_u64 v[220:221], s[20:21], 0, v[6:7]
	global_load_dword v210, v[220:221], off
	v_lshl_add_u64 v[220:221], s[76:77], 0, v[6:7]
	global_load_dword v211, v[220:221], off
	s_add_u32 s20, s20, 0x8000
	s_addc_u32 s21, s21, 0
	s_add_u32 s76, s76, 0x8000
	s_addc_u32 s77, s77, 0
	v_lshl_add_u64 v[220:221], s[20:21], 0, v[6:7]
	global_load_dword v212, v[220:221], off
	v_lshl_add_u64 v[220:221], s[76:77], 0, v[6:7]
	global_load_dword v213, v[220:221], off
	s_add_u32 s20, s20, 0x8000
	s_addc_u32 s21, s21, 0
	s_add_u32 s76, s76, 0x8000
	s_addc_u32 s77, s77, 0
	v_lshl_add_u64 v[220:221], s[20:21], 0, v[6:7]
	global_load_dword v214, v[220:221], off
	v_lshl_add_u64 v[220:221], s[76:77], 0, v[6:7]
	global_load_dword v215, v[220:221], off
	s_add_u32 s20, s20, 0x8000
	s_addc_u32 s21, s21, 0
	s_add_u32 s76, s76, 0x8000
	s_addc_u32 s77, s77, 0
	v_lshl_add_u64 v[220:221], s[20:21], 0, v[6:7]
	global_load_dword v216, v[220:221], off
	v_lshl_add_u64 v[220:221], s[76:77], 0, v[6:7]
	global_load_dword v217, v[220:221], off
	s_add_u32 s20, s20, 0x8000
	s_addc_u32 s21, s21, 0
	s_add_u32 s76, s76, 0x8000
	s_addc_u32 s77, s77, 0
	v_lshl_add_u64 v[220:221], s[20:21], 0, v[6:7]
	global_load_dword v218, v[220:221], off
	v_lshl_add_u64 v[220:221], s[76:77], 0, v[6:7]
	global_load_dword v219, v[220:221], off
	s_sub_u32 s20, s20, 0x38000
	s_subb_u32 s21, s21, 0
	s_sub_u32 s76, s76, 0x38000
	s_subb_u32 s77, s77, 0
	s_waitcnt vmcnt(15)
	v_cvt_pk_bf16_f32 v3, v204, s0
	ds_write_b16 v222, v3 offset:0
	s_waitcnt vmcnt(14)
	v_cvt_pk_bf16_f32 v9, v205, s0
	ds_write_b16 v223, v9 offset:0
	s_waitcnt vmcnt(13)
	v_cvt_pk_bf16_f32 v3, v206, s0
	ds_write_b16 v222, v3 offset:16
	s_waitcnt vmcnt(12)
	v_cvt_pk_bf16_f32 v9, v207, s0
	ds_write_b16 v223, v9 offset:16
	s_waitcnt vmcnt(11)
	v_cvt_pk_bf16_f32 v3, v208, s0
	ds_write_b16 v222, v3 offset:32
	s_waitcnt vmcnt(10)
	v_cvt_pk_bf16_f32 v9, v209, s0
	ds_write_b16 v223, v9 offset:32
	s_waitcnt vmcnt(9)
	v_cvt_pk_bf16_f32 v3, v210, s0
	ds_write_b16 v222, v3 offset:48
	s_waitcnt vmcnt(8)
	v_cvt_pk_bf16_f32 v9, v211, s0
	ds_write_b16 v223, v9 offset:48
	s_waitcnt vmcnt(7)
	v_cvt_pk_bf16_f32 v3, v212, s0
	ds_write_b16 v222, v3 offset:64
	s_waitcnt vmcnt(6)
	v_cvt_pk_bf16_f32 v9, v213, s0
	ds_write_b16 v223, v9 offset:64
	s_waitcnt vmcnt(5)
	v_cvt_pk_bf16_f32 v3, v214, s0
	ds_write_b16 v222, v3 offset:80
	s_waitcnt vmcnt(4)
	v_cvt_pk_bf16_f32 v9, v215, s0
	ds_write_b16 v223, v9 offset:80
	s_waitcnt vmcnt(3)
	v_cvt_pk_bf16_f32 v3, v216, s0
	ds_write_b16 v222, v3 offset:96
	s_waitcnt vmcnt(2)
	v_cvt_pk_bf16_f32 v9, v217, s0
	ds_write_b16 v223, v9 offset:96
	s_waitcnt vmcnt(1)
	v_cvt_pk_bf16_f32 v3, v218, s0
	ds_write_b16 v222, v3 offset:112
	s_waitcnt vmcnt(0)
	v_cvt_pk_bf16_f32 v9, v219, s0
	ds_write_b16 v223, v9 offset:112

; __device__ __forceinline__ unsigned cvt_pk_bf16(float lo, float hi) { return pk2(lo, hi); }
;     __device__ __forceinline__ void operator()(f32x4 (&acc)[2][2][4][2], const Unit& u, int wr, int wc, int fr, int fq) const {
;     ...
;                     for (int m = 0; m < 4; ++m) {
;                         const f32x2 pvm = f0 ? (m == 0 ? pe : ps[m == 0 ? 0 : m - 1]) : ps[m];
;                         const f32x2 nvm = f15 ? (m == 3 ? ne : ns[m == 3 ? 3 : m + 1]) : ns[m];
;                         f32x2 cu = w1 * c[m] + bb; cu = w0 * pvm + cu; cu = w2 * nvm + cu;
;                         f32x2 tq = (cu * cu) * cu; tq = tq * 0.044715f + cu;
;                         const f32x2 ea = tq * (-2.3022082f);
;                         f32x2 dn; dn.x = __builtin_amdgcn_exp2f(ea.x); dn.y = __builtin_amdgcn_exp2f(ea.y); dn = dn + 1.0f;
;                         f32x2 rc; rc.x = __builtin_amdgcn_rcpf(dn.x); rc.y = __builtin_amdgcn_rcpf(dn.y);
;                         const f32x2 vv = {acc[ai][1][m][n][2 * p], acc[ai][1][m][n][2 * p + 1]};
;                         const f32x2 o = (cu * rc) * vv;
;                         res[m][2 * p] = o.x; res[m][2 * p + 1] = o.y; }
;                 }
; #pragma unroll
;                 for (int m = 0; m < 4; ++m) { const int j = ai * 128 + wr * 64 + m * 16 + fr;
;                     u32x2 w; w.x = cvt_pk_bf16(res[m][0], res[m][1]); w.y = cvt_pk_bf16(res[m][2], res[m][3]);
;                     if (j >= 1 && j <= 254) *(u32x2*)(act + (size_t)(rowt + j) * FFN + colg + 4 * n) = w; }
.LBB0_454:
	v_mov_b32_e32 v58, v102
	v_mov_b32_e32 v59, v102
	v_pk_mul_f32 v[56:57], v[56:57], v[58:59]
	s_waitcnt vmcnt(0)
	v_pk_fma_f32 v[58:59], v[72:73], v[88:89], v[96:97]
	s_waitcnt lgkmcnt(7)
	v_cndmask_b32_e64 v62, v130, v140, s[36:37]
	s_waitcnt lgkmcnt(6)
	v_cndmask_b32_e64 v63, v131, v141, s[36:37]
	s_waitcnt lgkmcnt(1)
	v_cndmask_b32_e64 v64, v145, v132, s[38:39]
	s_waitcnt lgkmcnt(0)
	v_cndmask_b32_e64 v65, v146, v134, s[38:39]
	v_pk_fma_f32 v[58:59], v[80:81], v[62:63], v[58:59]
	s_mov_b32 s24, 0x3d372713
	v_pk_fma_f32 v[58:59], v[84:85], v[64:65], v[58:59]
	s_mov_b32 s62, 0xc0135761
	v_pk_mul_f32 v[62:63], v[58:59], v[58:59]
	v_pk_fma_f32 v[60:61], v[70:71], v[86:87], v[94:95]
	v_pk_mul_f32 v[62:63], v[58:59], v[62:63]
	v_pk_mul_f32 v[54:55], v[54:55], v[102:103]
	v_pk_fma_f32 v[62:63], v[62:63], s[24:25], v[58:59] op_sel_hi:[1,0,1]
	s_movk_i32 s15, 0x1600
	v_pk_mul_f32 v[62:63], v[62:63], s[62:63] op_sel_hi:[1,0]
	s_nop 0
	v_exp_f32_e32 v62, v62
	v_exp_f32_e32 v63, v63
	s_nop 0
	v_pk_add_f32 v[62:63], v[62:63], 1.0 op_sel_hi:[1,0]
	s_nop 0
	v_rcp_f32_e32 v62, v62
	v_rcp_f32_e32 v63, v63
	s_nop 0
	v_pk_mul_f32 v[58:59], v[58:59], v[62:63]
	s_nop 0
	v_pk_mul_f32 v[56:57], v[56:57], v[58:59]
	v_cndmask_b32_e64 v58, v120, v136, s[36:37]
	v_cndmask_b32_e64 v59, v121, v137, s[36:37]
	v_cndmask_b32_e64 v62, v138, v126, s[38:39]
	v_cndmask_b32_e64 v63, v139, v128, s[38:39]
	v_pk_fma_f32 v[58:59], v[78:79], v[58:59], v[60:61]
	v_cvt_pk_bf16_f32 v57, v56, v57
	v_pk_fma_f32 v[58:59], v[82:83], v[62:63], v[58:59]
	s_nop 0
	v_pk_mul_f32 v[60:61], v[58:59], v[58:59]
	s_nop 0
	v_pk_mul_f32 v[60:61], v[58:59], v[60:61]
	s_nop 0
	v_pk_fma_f32 v[60:61], v[60:61], s[24:25], v[58:59] op_sel_hi:[1,0,1]
	s_nop 0
	v_pk_mul_f32 v[60:61], v[60:61], s[62:63] op_sel_hi:[1,0]
	s_nop 0
	v_exp_f32_e32 v60, v60
	v_exp_f32_e32 v61, v61
	s_nop 0
	v_pk_add_f32 v[60:61], v[60:61], 1.0 op_sel_hi:[1,0]
	s_nop 0
	v_rcp_f32_e32 v60, v60
	v_rcp_f32_e32 v61, v61
	s_nop 0
	v_pk_mul_f32 v[58:59], v[58:59], v[60:61]
	s_nop 0
	v_pk_mul_f32 v[54:55], v[54:55], v[58:59]
	s_nop 0
	v_cvt_pk_bf16_f32 v56, v54, v55
	v_mov_b64_e32 v[54:55], s[76:77]
	v_mad_i64_i32 v[54:55], s[62:63], v143, s15, v[54:55]
	v_lshl_add_u64 v[54:55], v[162:163], 1, v[54:55]
	global_store_dwordx2 v[54:55], v[56:57], off offset:8
	s_or_b64 exec, exec, s[12:13]
	s_and_saveexec_b64 s[12:13], s[46:47]
	s_cbranch_execnz .LBB0_458
	s_branch .LBB0_459
.Ltramp_b1014:
	s_branch .LBB0_1014

; __device__ __forceinline__ unsigned cvt_pk_bf16(float lo, float hi) { return pk2(lo, hi); }
;     __device__ __forceinline__ void operator()(f32x4 (&acc)[2][2][4][2], const Unit& u, int wr, int wc, int fr, int fq) const {
;     ...
;                 for (int m = 0; m < 4; ++m) { const int j = ai * 128 + wr * 64 + m * 16 + fr;
;                     u32x2 w; w.x = cvt_pk_bf16(res[m][0], res[m][1]); w.y = cvt_pk_bf16(res[m][2], res[m][3]);
;                     if (j >= 1 && j <= 254) *(u32x2*)(act + (size_t)(rowt + j) * FFN + colg + 4 * n) = w; }
.Ltramp_b33:
	s_branch .LBB0_33
.LBB0_455:
	s_or_b64 exec, exec, s[12:13]
	s_and_saveexec_b64 s[12:13], s[42:43]
	s_cbranch_execz .LBB0_453

; __device__ __forceinline__ float bf2f(unsigned short v) { return __uint_as_float(((unsigned)v) << 16); }
; __device__ __forceinline__ float sigmoidf_(float x) { return __builtin_amdgcn_rcpf(1.0f + __expf(-x)); }
; template <bool PA>
; __device__ __forceinline__ void hgrn_scan(unsigned char* lds, const bf16* Q, const bf16* FFb, const bf16* FBb, const bf16* Ib, bf16* OFb, bf16* OBb, const float* lbp, float* segm, int slab, int tid) {
;     ...
;             for (int jj = 0; jj < 16; ++jj) { const float f = bf2f(fraw[jj]); const float fg = lb + (1.0f - lb) * sigmoidf_(f); run *= fg; bl[jj] = run; kvv[jj] = 1.0f - fg; qv[jj] = bf2f(qraw[jj]); }
;             tot[seg * 128 + c] = run;
;             { const size_t row = cbase + (dir ? 63 - jr : jr);
;               const u32x4_t w0 = *(const u32x4_t*)(Ib + row * 1024 + head * 128 + part * 16), w1 = *(const u32x4_t*)(Ib + row * 1024 + head * 128 + part * 16 + 8);
;               const unsigned wa[8] = {w0.x, w0.y, w0.z, w0.w, w1.x, w1.y, w1.z, w1.w};
; #pragma unroll
;               for (int q = 0; q < 8; ++q) { iT[(part * 16 + 2 * q) * 72 + jr] = (bf16)(wa[q] & 0xffff); iT[(part * 16 + 2 * q + 1) * 72 + jr] = (bf16)(wa[q] >> 16); } }
.LBB0_676:
	v_lshlrev_b32_e32 v34, 16, v182
	v_mul_f32_e32 v34, 0xbfb8aa3b, v34
	v_exp_f32_e32 v34, v34
	s_add_i32 s12, s24, 1
	s_and_b64 s[10:11], s[56:57], exec
	s_cselect_b32 s10, s65, s12
	v_add_f32_e32 v34, 1.0, v34
	v_rcp_f32_e32 v34, v34
	v_lshl_add_u32 v38, s10, 6, v213
	v_ashrrev_i32_e32 v39, 31, v38
	v_lshlrev_b64 v[230:231], 11, v[38:39]
	v_lshl_add_u64 v[230:231], v[82:83], 0, v[230:231]
	global_load_dwordx4 v[222:225], v[230:231], off
	global_load_dwordx4 v[226:229], v[230:231], off offset:16
	s_add_i32 s65, s65, 1
	v_fma_f32 v58, v211, v34, v210
	v_lshlrev_b32_e32 v34, 16, v184
	v_mul_f32_e32 v34, 0xbfb8aa3b, v34
	v_exp_f32_e32 v34, v34
	s_cmp_ge_i32 s65, s67
	s_cselect_b64 s[10:11], -1, 0
	s_and_b64 vcc, exec, s[10:11]
	v_add_f32_e32 v34, 1.0, v34
	v_rcp_f32_e32 v34, v34
	s_nop 0
	v_fma_f32 v239, v211, v34, v210
	v_lshlrev_b32_e32 v34, 16, v185
	v_mul_f32_e32 v34, 0xbfb8aa3b, v34
	v_exp_f32_e32 v34, v34
	v_mul_f32_e32 v64, v58, v239
	v_add_f32_e32 v34, 1.0, v34
	v_rcp_f32_e32 v34, v34
	s_nop 0
	v_fma_f32 v240, v211, v34, v210
	v_lshlrev_b32_e32 v34, 16, v186
	v_mul_f32_e32 v34, 0xbfb8aa3b, v34
	v_exp_f32_e32 v34, v34
	v_mul_f32_e32 v62, v64, v240
	v_add_f32_e32 v34, 1.0, v34
	v_rcp_f32_e32 v34, v34
	s_nop 0
	v_fma_f32 v241, v211, v34, v210
	v_lshlrev_b32_e32 v34, 16, v193
	v_mul_f32_e32 v34, 0xbfb8aa3b, v34
	v_exp_f32_e32 v34, v34
	v_mul_f32_e32 v234, v62, v241
	v_add_f32_e32 v34, 1.0, v34
	v_rcp_f32_e32 v34, v34
	s_nop 0
	v_fma_f32 v242, v211, v34, v210
	v_lshlrev_b32_e32 v34, 16, v195
	v_mul_f32_e32 v34, 0xbfb8aa3b, v34
	v_exp_f32_e32 v34, v34
	v_mul_f32_e32 v237, v234, v242
	v_add_f32_e32 v34, 1.0, v34
	v_rcp_f32_e32 v34, v34
	s_nop 0
	v_fma_f32 v243, v211, v34, v210
	v_lshlrev_b32_e32 v34, 16, v205
	v_mul_f32_e32 v34, 0xbfb8aa3b, v34
	v_exp_f32_e32 v34, v34
	v_mul_f32_e32 v238, v237, v243
	v_add_f32_e32 v34, 1.0, v34
	v_rcp_f32_e32 v34, v34
	s_nop 0
	v_fma_f32 v244, v211, v34, v210
	v_lshlrev_b32_e32 v34, 16, v206
	v_mul_f32_e32 v34, 0xbfb8aa3b, v34
	v_exp_f32_e32 v34, v34
	v_mul_f32_e32 v236, v238, v244
	v_add_f32_e32 v34, 1.0, v34
	v_rcp_f32_e32 v34, v34
	s_nop 0
	v_fma_f32 v245, v211, v34, v210
	v_lshlrev_b32_e32 v34, 16, v207
	v_mul_f32_e32 v34, 0xbfb8aa3b, v34
	v_exp_f32_e32 v34, v34
	v_mul_f32_e32 v235, v236, v245
	v_add_f32_e32 v34, 1.0, v34
	v_rcp_f32_e32 v34, v34
	s_nop 0
	v_fma_f32 v246, v211, v34, v210
	v_lshlrev_b32_e32 v34, 16, v208
	v_mul_f32_e32 v34, 0xbfb8aa3b, v34
	v_exp_f32_e32 v34, v34
	v_mul_f32_e32 v233, v235, v246
	v_add_f32_e32 v34, 1.0, v34
	v_rcp_f32_e32 v34, v34
	s_nop 0
	v_fma_f32 v247, v211, v34, v210
	v_lshlrev_b32_e32 v34, 16, v209
	v_mul_f32_e32 v34, 0xbfb8aa3b, v34
	v_exp_f32_e32 v34, v34
	v_mul_f32_e32 v65, v233, v247
	v_add_f32_e32 v34, 1.0, v34
	v_rcp_f32_e32 v34, v34
	s_nop 0
	v_fma_f32 v248, v211, v34, v210
	v_lshlrev_b32_e32 v34, 16, v212
	v_mul_f32_e32 v34, 0xbfb8aa3b, v34
	v_exp_f32_e32 v34, v34
	v_mul_f32_e32 v63, v65, v248
	v_add_f32_e32 v34, 1.0, v34
	v_rcp_f32_e32 v34, v34
	s_nop 0
	v_fma_f32 v249, v211, v34, v210
	v_lshlrev_b32_e32 v34, 16, v214
	v_mul_f32_e32 v34, 0xbfb8aa3b, v34
	v_exp_f32_e32 v34, v34
	v_mul_f32_e32 v61, v63, v249
	v_add_f32_e32 v34, 1.0, v34
	v_rcp_f32_e32 v34, v34
	s_nop 0
	v_fma_f32 v250, v211, v34, v210
	v_lshlrev_b32_e32 v34, 16, v217
	v_mul_f32_e32 v34, 0xbfb8aa3b, v34
	v_exp_f32_e32 v34, v34
	v_mul_f32_e32 v60, v61, v250
	v_add_f32_e32 v34, 1.0, v34
	v_rcp_f32_e32 v34, v34
	s_nop 0
	v_fma_f32 v251, v211, v34, v210
	v_lshlrev_b32_e32 v34, 16, v219
	v_mul_f32_e32 v34, 0xbfb8aa3b, v34
	v_exp_f32_e32 v34, v34
	v_mul_f32_e32 v59, v60, v251
	v_add_f32_e32 v34, 1.0, v34
	v_rcp_f32_e32 v34, v34
	s_nop 0
	v_fma_f32 v252, v211, v34, v210
	s_waitcnt vmcnt(2)
	v_lshlrev_b32_e32 v34, 16, v220
	v_mul_f32_e32 v34, 0xbfb8aa3b, v34
	v_exp_f32_e32 v34, v34
	v_mul_f32_e32 v57, v59, v252
	v_add_f32_e32 v34, 1.0, v34
	v_rcp_f32_e32 v34, v34
	s_nop 0
	v_fma_f32 v146, v211, v34, v210
	v_mul_f32_e32 v56, v57, v146
	ds_write_b32 v90, v56
	s_waitcnt vmcnt(1)
	ds_write_b16 v129, v222 offset:62464
	ds_write_b16_d16_hi v130, v222 offset:62608
	ds_write_b16 v129, v223 offset:62752
	ds_write_b16_d16_hi v130, v223 offset:62896
	ds_write_b16 v129, v224 offset:63040
	ds_write_b16_d16_hi v130, v224 offset:63184
	ds_write_b16 v129, v225 offset:63328
	ds_write_b16_d16_hi v130, v225 offset:63472
	s_waitcnt vmcnt(0)
	ds_write_b16 v129, v226 offset:63616
	ds_write_b16_d16_hi v130, v226 offset:63760
	ds_write_b16 v129, v227 offset:63904
	ds_write_b16_d16_hi v130, v227 offset:64048
	ds_write_b16 v129, v228 offset:64192
	ds_write_b16_d16_hi v130, v228 offset:64336
	ds_write_b16 v129, v229 offset:64480
	ds_write_b16_d16_hi v130, v229 offset:64624
	s_cbranch_vccnz .LBB0_678
; template <bool PA>
; __device__ __forceinline__ void hgrn_scan(unsigned char* lds, const bf16* Q, const bf16* FFb, const bf16* FBb, const bf16* Ib, bf16* OFb, bf16* OBb, const float* lbp, float* segm, int slab, int tid) {
;     ...
;             if (p + 1 < p1) { const int nb = seqbase + (dir ? nch - 2 - p : p + 1) * 64;
; #pragma unroll
;                 for (int jj = 0; jj < 16; ++jj) { const int j = 16 * seg + jj; const unsigned bo = ((unsigned)(nb + (dir ? 63 - j : j)) * 1024u + (unsigned)hc) * 2u; qraw[jj] = PA ? (unsigned short)0 : *(const unsigned short*)((const char*)Q + bo); fraw[jj] = *(const unsigned short*)((const char*)Fp + bo); } }
	s_and_b64 s[12:13], s[56:57], exec
	s_cselect_b32 s12, s65, s24
	s_lshl_b32 s12, s12, 6
	s_add_i32 s12, s12, s66
	v_add_u32_e32 v34, s12, v0
	v_lshl_or_b32 v34, v34, 11, v175
	v_add_u32_e32 v35, s12, v176
	v_add_u32_e32 v36, s12, v177
	v_add_u32_e32 v37, s12, v178
	v_lshl_or_b32 v35, v35, 11, v175
	v_lshl_or_b32 v36, v36, 11, v175
	v_lshl_or_b32 v37, v37, 11, v175
	global_load_ushort v81, v34, s[16:17]
	global_load_ushort v182, v34, s[8:9]
	global_load_ushort v215, v35, s[16:17]
	global_load_ushort v184, v35, s[8:9]
	global_load_ushort v216, v36, s[16:17]
	global_load_ushort v185, v36, s[8:9]
	global_load_ushort v218, v37, s[16:17]
	global_load_ushort v186, v37, s[8:9]
	v_add_u32_e32 v34, s12, v179
	v_lshl_or_b32 v34, v34, 11, v175
	v_add_u32_e32 v35, s12, v180
	v_add_u32_e32 v36, s12, v181
	v_add_u32_e32 v37, s12, v183
	v_lshl_or_b32 v35, v35, 11, v175
	v_lshl_or_b32 v36, v36, 11, v175
	v_lshl_or_b32 v37, v37, 11, v175
	global_load_ushort v221, v34, s[16:17]
	global_load_ushort v193, v34, s[8:9]
	global_load_ushort v222, v35, s[16:17]
	global_load_ushort v195, v35, s[8:9]
	global_load_ushort v223, v36, s[16:17]
	global_load_ushort v205, v36, s[8:9]
	global_load_ushort v224, v37, s[16:17]
	global_load_ushort v206, v37, s[8:9]
	v_add_u32_e32 v34, s12, v187
	v_lshl_or_b32 v34, v34, 11, v175
	v_add_u32_e32 v35, s12, v188
	v_add_u32_e32 v36, s12, v189
	v_add_u32_e32 v37, s12, v190
	v_lshl_or_b32 v35, v35, 11, v175
	v_lshl_or_b32 v36, v36, 11, v175
	v_lshl_or_b32 v37, v37, 11, v175
	global_load_ushort v225, v34, s[16:17]
	global_load_ushort v207, v34, s[8:9]
	global_load_ushort v226, v35, s[16:17]
	global_load_ushort v208, v35, s[8:9]
	global_load_ushort v227, v36, s[16:17]
	global_load_ushort v209, v36, s[8:9]
	global_load_ushort v228, v37, s[16:17]
	global_load_ushort v212, v37, s[8:9]
	v_add_u32_e32 v34, s12, v191
	v_lshl_or_b32 v34, v34, 11, v175
	v_add_u32_e32 v35, s12, v192
	v_add_u32_e32 v36, s12, v194
	v_add_u32_e32 v37, s12, v204
	v_lshl_or_b32 v35, v35, 11, v175
	v_lshl_or_b32 v36, v36, 11, v175
	v_lshl_or_b32 v37, v37, 11, v175
	global_load_ushort v229, v34, s[16:17]
	global_load_ushort v214, v34, s[8:9]
	global_load_ushort v230, v35, s[16:17]
	global_load_ushort v217, v35, s[8:9]
	global_load_ushort v231, v36, s[16:17]
	global_load_ushort v219, v36, s[8:9]
	global_load_ushort v232, v37, s[16:17]
	global_load_ushort v220, v37, s[8:9]

; __device__ __forceinline__ void tr_item(const float* W, int N, int Klim, int k0, int n0, bf16* WT, int ldk, int drow, int dcol, const float* sc, float* scr, int lane, const float* sc2 = nullptr, bool nts = true) {
;     if (k0 + 64 <= Klim) {
; #pragma unroll 8
;         for (int i = 0; i < 32; ++i) { const int kk = 2 * i + (lane >> 5); scr[kk * 33 + (lane & 31)] = __builtin_nontemporal_load(W + (size_t)(k0 + kk) * N + n0 + (lane & 31)); }
.LBB0_770:
	v_lshl_add_u64 v[136:137], v[46:47], 0, s[50:51]
	global_load_dword v112, v[136:137], off nt
	v_lshl_add_u64 v[138:139], v[44:45], 0, s[50:51]
	global_load_dword v113, v[138:139], off nt
	v_lshl_add_u64 v[136:137], v[42:43], 0, s[50:51]
	global_load_dword v114, v[136:137], off nt
	v_lshl_add_u64 v[138:139], v[40:41], 0, s[50:51]
	global_load_dword v115, v[138:139], off nt
	v_lshl_add_u64 v[136:137], v[38:39], 0, s[50:51]
	global_load_dword v116, v[136:137], off nt
	v_lshl_add_u64 v[138:139], v[8:9], 0, s[50:51]
	global_load_dword v117, v[138:139], off nt
	v_lshl_add_u64 v[136:137], v[6:7], 0, s[50:51]
	global_load_dword v118, v[136:137], off nt
	v_lshl_add_u64 v[138:139], v[4:5], 0, s[50:51]
	global_load_dword v119, v[138:139], off nt
	s_add_u32 s50, s50, 0x10000
	s_addc_u32 s51, s51, 0
	v_lshl_add_u64 v[136:137], v[46:47], 0, s[50:51]
	global_load_dword v120, v[136:137], off nt
	v_lshl_add_u64 v[138:139], v[44:45], 0, s[50:51]
	global_load_dword v121, v[138:139], off nt
	v_lshl_add_u64 v[136:137], v[42:43], 0, s[50:51]
	global_load_dword v122, v[136:137], off nt
	v_lshl_add_u64 v[138:139], v[40:41], 0, s[50:51]
	global_load_dword v123, v[138:139], off nt
	v_lshl_add_u64 v[136:137], v[38:39], 0, s[50:51]
	global_load_dword v124, v[136:137], off nt
	v_lshl_add_u64 v[138:139], v[8:9], 0, s[50:51]
	global_load_dword v125, v[138:139], off nt
	v_lshl_add_u64 v[136:137], v[6:7], 0, s[50:51]
	global_load_dword v126, v[136:137], off nt
	v_lshl_add_u64 v[138:139], v[4:5], 0, s[50:51]
	global_load_dword v127, v[138:139], off nt
	s_add_u32 s50, s50, 0x10000
	s_addc_u32 s51, s51, 0
	v_lshl_add_u64 v[136:137], v[46:47], 0, s[50:51]
	global_load_dword v128, v[136:137], off nt
	v_lshl_add_u64 v[138:139], v[44:45], 0, s[50:51]
	global_load_dword v129, v[138:139], off nt
	v_lshl_add_u64 v[136:137], v[42:43], 0, s[50:51]
	global_load_dword v130, v[136:137], off nt
	v_lshl_add_u64 v[138:139], v[40:41], 0, s[50:51]
	global_load_dword v131, v[138:139], off nt
	v_lshl_add_u64 v[136:137], v[38:39], 0, s[50:51]
	global_load_dword v132, v[136:137], off nt
	v_lshl_add_u64 v[138:139], v[8:9], 0, s[50:51]
	global_load_dword v133, v[138:139], off nt
	v_lshl_add_u64 v[136:137], v[6:7], 0, s[50:51]
	global_load_dword v134, v[136:137], off nt
	v_lshl_add_u64 v[138:139], v[4:5], 0, s[50:51]
	global_load_dword v135, v[138:139], off nt
	s_add_u32 s50, s50, 0x10000
	s_addc_u32 s51, s51, 0
	v_lshl_add_u64 v[50:51], v[46:47], 0, s[50:51]
	v_lshl_add_u64 v[94:95], v[44:45], 0, s[50:51]
	v_lshl_add_u64 v[96:97], v[42:43], 0, s[50:51]
	v_lshl_add_u64 v[98:99], v[40:41], 0, s[50:51]
	v_lshl_add_u64 v[100:101], v[38:39], 0, s[50:51]
	v_lshl_add_u64 v[102:103], v[8:9], 0, s[50:51]
	v_lshl_add_u64 v[104:105], v[6:7], 0, s[50:51]
	v_lshl_add_u64 v[106:107], v[4:5], 0, s[50:51]
	global_load_dword v49, v[50:51], off nt
	s_nop 0
	global_load_dword v50, v[94:95], off nt
	global_load_dword v51, v[96:97], off nt
	s_nop 0
	global_load_dword v94, v[98:99], off nt
	global_load_dword v95, v[100:101], off nt
	global_load_dword v96, v[102:103], off nt
	global_load_dword v97, v[104:105], off nt
	s_nop 0
	global_load_dword v98, v[106:107], off nt
	s_add_u32 s50, s50, 0x10000
	s_addc_u32 s51, s51, 0
	v_add_u32_e32 v99, 0x400, v3
	s_waitcnt vmcnt(30)
	ds_write2_b32 v3, v112, v113 offset1:66
	s_waitcnt vmcnt(28)
	ds_write2_b32 v3, v114, v115 offset0:132 offset1:198
	s_waitcnt vmcnt(26)
	ds_write2_b32 v99, v116, v117 offset0:8 offset1:74
	s_waitcnt vmcnt(24)
	ds_write2_b32 v99, v118, v119 offset0:140 offset1:206
	v_add_u32_e32 v3, 0x840, v3
	v_add_u32_e32 v99, 0x400, v3
	s_waitcnt vmcnt(22)
	ds_write2_b32 v3, v120, v121 offset1:66
	s_waitcnt vmcnt(20)
	ds_write2_b32 v3, v122, v123 offset0:132 offset1:198
	s_waitcnt vmcnt(18)
	ds_write2_b32 v99, v124, v125 offset0:8 offset1:74
	s_waitcnt vmcnt(16)
	ds_write2_b32 v99, v126, v127 offset0:140 offset1:206
	v_add_u32_e32 v3, 0x840, v3
	v_add_u32_e32 v99, 0x400, v3
	s_waitcnt vmcnt(14)
	ds_write2_b32 v3, v128, v129 offset1:66
	s_waitcnt vmcnt(12)
	ds_write2_b32 v3, v130, v131 offset0:132 offset1:198
	s_waitcnt vmcnt(10)
	ds_write2_b32 v99, v132, v133 offset0:8 offset1:74
	s_waitcnt vmcnt(8)
	ds_write2_b32 v99, v134, v135 offset0:140 offset1:206
	v_add_u32_e32 v3, 0x840, v3
	v_add_u32_e32 v99, 0x400, v3
	s_waitcnt vmcnt(6)
	ds_write2_b32 v3, v49, v50 offset1:66
	s_waitcnt vmcnt(4)
	ds_write2_b32 v3, v51, v94 offset0:132 offset1:198
	s_waitcnt vmcnt(2)
	ds_write2_b32 v99, v95, v96 offset0:8 offset1:74
	s_waitcnt vmcnt(0)
	ds_write2_b32 v99, v97, v98 offset0:140 offset1:206
	v_add_u32_e32 v3, 0x840, v3

; __device__ __forceinline__ void tr_item(const float* W, int N, int Klim, int k0, int n0, bf16* WT, int ldk, int drow, int dcol, const float* sc, float* scr, int lane, const float* sc2 = nullptr, bool nts = true) {
;     if (k0 + 64 <= Klim) {
; #pragma unroll 8
;         for (int i = 0; i < 32; ++i) { const int kk = 2 * i + (lane >> 5); scr[kk * 33 + (lane & 31)] = __builtin_nontemporal_load(W + (size_t)(k0 + kk) * N + n0 + (lane & 31)); }
.LBB0_818:
	v_lshl_add_u64 v[136:137], v[48:49], 0, s[52:53]
	global_load_dword v112, v[136:137], off nt
	v_lshl_add_u64 v[138:139], v[46:47], 0, s[52:53]
	global_load_dword v113, v[138:139], off nt
	v_lshl_add_u64 v[136:137], v[44:45], 0, s[52:53]
	global_load_dword v114, v[136:137], off nt
	v_lshl_add_u64 v[138:139], v[42:43], 0, s[52:53]
	global_load_dword v115, v[138:139], off nt
	v_lshl_add_u64 v[136:137], v[8:9], 0, s[52:53]
	global_load_dword v116, v[136:137], off nt
	v_lshl_add_u64 v[138:139], v[6:7], 0, s[52:53]
	global_load_dword v117, v[138:139], off nt
	v_lshl_add_u64 v[136:137], v[4:5], 0, s[52:53]
	global_load_dword v118, v[136:137], off nt
	v_lshl_add_u64 v[138:139], v[2:3], 0, s[52:53]
	global_load_dword v119, v[138:139], off nt
	s_add_u32 s52, s52, 0x2800
	s_addc_u32 s53, s53, 0
	v_lshl_add_u64 v[136:137], v[48:49], 0, s[52:53]
	global_load_dword v120, v[136:137], off nt
	v_lshl_add_u64 v[138:139], v[46:47], 0, s[52:53]
	global_load_dword v121, v[138:139], off nt
	v_lshl_add_u64 v[136:137], v[44:45], 0, s[52:53]
	global_load_dword v122, v[136:137], off nt
	v_lshl_add_u64 v[138:139], v[42:43], 0, s[52:53]
	global_load_dword v123, v[138:139], off nt
	v_lshl_add_u64 v[136:137], v[8:9], 0, s[52:53]
	global_load_dword v124, v[136:137], off nt
	v_lshl_add_u64 v[138:139], v[6:7], 0, s[52:53]
	global_load_dword v125, v[138:139], off nt
	v_lshl_add_u64 v[136:137], v[4:5], 0, s[52:53]
	global_load_dword v126, v[136:137], off nt
	v_lshl_add_u64 v[138:139], v[2:3], 0, s[52:53]
	global_load_dword v127, v[138:139], off nt
	s_add_u32 s52, s52, 0x2800
	s_addc_u32 s53, s53, 0
	v_lshl_add_u64 v[136:137], v[48:49], 0, s[52:53]
	global_load_dword v128, v[136:137], off nt
	v_lshl_add_u64 v[138:139], v[46:47], 0, s[52:53]
	global_load_dword v129, v[138:139], off nt
	v_lshl_add_u64 v[136:137], v[44:45], 0, s[52:53]
	global_load_dword v130, v[136:137], off nt
	v_lshl_add_u64 v[138:139], v[42:43], 0, s[52:53]
	global_load_dword v131, v[138:139], off nt
	v_lshl_add_u64 v[136:137], v[8:9], 0, s[52:53]
	global_load_dword v132, v[136:137], off nt
	v_lshl_add_u64 v[138:139], v[6:7], 0, s[52:53]
	global_load_dword v133, v[138:139], off nt
	v_lshl_add_u64 v[136:137], v[4:5], 0, s[52:53]
	global_load_dword v134, v[136:137], off nt
	v_lshl_add_u64 v[138:139], v[2:3], 0, s[52:53]
	global_load_dword v135, v[138:139], off nt
	s_add_u32 s52, s52, 0x2800
	s_addc_u32 s53, s53, 0
	v_lshl_add_u64 v[50:51], v[48:49], 0, s[52:53]
	v_lshl_add_u64 v[94:95], v[46:47], 0, s[52:53]
	v_lshl_add_u64 v[96:97], v[44:45], 0, s[52:53]
	v_lshl_add_u64 v[98:99], v[42:43], 0, s[52:53]
	v_lshl_add_u64 v[100:101], v[8:9], 0, s[52:53]
	v_lshl_add_u64 v[102:103], v[6:7], 0, s[52:53]
	v_lshl_add_u64 v[104:105], v[4:5], 0, s[52:53]
	v_lshl_add_u64 v[106:107], v[2:3], 0, s[52:53]
	global_load_dword v41, v[50:51], off nt
	s_nop 0
	global_load_dword v51, v[94:95], off nt
	s_nop 0
	global_load_dword v94, v[96:97], off nt
	global_load_dword v95, v[98:99], off nt
	s_nop 0
	global_load_dword v96, v[100:101], off nt
	global_load_dword v97, v[102:103], off nt
	global_load_dword v98, v[104:105], off nt
	global_load_dword v99, v[106:107], off nt
	s_add_u32 s52, s52, 0x2800
	s_addc_u32 s53, s53, 0
	v_add_u32_e32 v100, 0x400, v0
	s_waitcnt vmcnt(30)
	ds_write2_b32 v0, v112, v113 offset1:66
	s_waitcnt vmcnt(28)
	ds_write2_b32 v0, v114, v115 offset0:132 offset1:198
	s_waitcnt vmcnt(26)
	ds_write2_b32 v100, v116, v117 offset0:8 offset1:74
	s_waitcnt vmcnt(24)
	ds_write2_b32 v100, v118, v119 offset0:140 offset1:206
	v_add_u32_e32 v0, 0x840, v0
	v_add_u32_e32 v100, 0x400, v0
	s_waitcnt vmcnt(22)
	ds_write2_b32 v0, v120, v121 offset1:66
	s_waitcnt vmcnt(20)
	ds_write2_b32 v0, v122, v123 offset0:132 offset1:198
	s_waitcnt vmcnt(18)
	ds_write2_b32 v100, v124, v125 offset0:8 offset1:74
	s_waitcnt vmcnt(16)
	ds_write2_b32 v100, v126, v127 offset0:140 offset1:206
	v_add_u32_e32 v0, 0x840, v0
	v_add_u32_e32 v100, 0x400, v0
	s_waitcnt vmcnt(14)
	ds_write2_b32 v0, v128, v129 offset1:66
	s_waitcnt vmcnt(12)
	ds_write2_b32 v0, v130, v131 offset0:132 offset1:198
	s_waitcnt vmcnt(10)
	ds_write2_b32 v100, v132, v133 offset0:8 offset1:74
	s_waitcnt vmcnt(8)
	ds_write2_b32 v100, v134, v135 offset0:140 offset1:206
	v_add_u32_e32 v0, 0x840, v0
	v_add_u32_e32 v100, 0x400, v0
	s_waitcnt vmcnt(6)
	ds_write2_b32 v0, v41, v51 offset1:66
	s_waitcnt vmcnt(4)
	ds_write2_b32 v0, v94, v95 offset0:132 offset1:198
	s_waitcnt vmcnt(2)
	ds_write2_b32 v100, v96, v97 offset0:8 offset1:74
	s_waitcnt vmcnt(0)
	ds_write2_b32 v100, v98, v99 offset0:140 offset1:206
	v_add_u32_e32 v0, 0x840, v0

; __device__ __forceinline__ void tr_item(const float* W, int N, int Klim, int k0, int n0, bf16* WT, int ldk, int drow, int dcol, const float* sc, float* scr, int lane, const float* sc2 = nullptr, bool nts = true) {
;     if (k0 + 64 <= Klim) {
; #pragma unroll 8
;         for (int i = 0; i < 32; ++i) { const int kk = 2 * i + (lane >> 5); scr[kk * 33 + (lane & 31)] = __builtin_nontemporal_load(W + (size_t)(k0 + kk) * N + n0 + (lane & 31)); }
;     } else {
; #pragma unroll 8
;         for (int i = 0; i < 32; ++i) { const int kk = 2 * i + (lane >> 5); const int k = k0 + kk; float v = 0.f; if (k < Klim) v = W[(size_t)k * N + n0 + (lane & 31)]; scr[kk * 33 + (lane & 31)] = v; }
;     }
;     asm volatile("s_waitcnt lgkmcnt(0)" ::: "memory");
;     const int c = lane & 7;
;     f32x4_t sa = (f32x4_t){1.f, 1.f, 1.f, 1.f}, sb = sa;
;     if (sc) { sa = *(const f32x4_t*)(sc + k0 + 8 * c); sb = *(const f32x4_t*)(sc + k0 + 8 * c + 4);
;         if (sc2) { sa = sa - *(const f32x4_t*)(sc2 + k0 + 8 * c); sb = sb - *(const f32x4_t*)(sc2 + k0 + 8 * c + 4); } }
.LBB0_845:
	v_lshl_add_u64 v[136:137], v[44:45], 0, s[12:13]
	global_load_dword v112, v[136:137], off nt
	v_lshl_add_u64 v[138:139], v[42:43], 0, s[12:13]
	global_load_dword v113, v[138:139], off nt
	v_lshl_add_u64 v[136:137], v[40:41], 0, s[12:13]
	global_load_dword v114, v[136:137], off nt
	v_lshl_add_u64 v[138:139], v[38:39], 0, s[12:13]
	global_load_dword v115, v[138:139], off nt
	v_lshl_add_u64 v[136:137], v[8:9], 0, s[12:13]
	global_load_dword v116, v[136:137], off nt
	v_lshl_add_u64 v[138:139], v[6:7], 0, s[12:13]
	global_load_dword v117, v[138:139], off nt
	v_lshl_add_u64 v[136:137], v[4:5], 0, s[12:13]
	global_load_dword v118, v[136:137], off nt
	v_lshl_add_u64 v[138:139], v[2:3], 0, s[12:13]
	global_load_dword v119, v[138:139], off nt
	s_add_u32 s12, s12, 0x1000
	s_addc_u32 s13, s13, 0
	v_lshl_add_u64 v[136:137], v[44:45], 0, s[12:13]
	global_load_dword v120, v[136:137], off nt
	v_lshl_add_u64 v[138:139], v[42:43], 0, s[12:13]
	global_load_dword v121, v[138:139], off nt
	v_lshl_add_u64 v[136:137], v[40:41], 0, s[12:13]
	global_load_dword v122, v[136:137], off nt
	v_lshl_add_u64 v[138:139], v[38:39], 0, s[12:13]
	global_load_dword v123, v[138:139], off nt
	v_lshl_add_u64 v[136:137], v[8:9], 0, s[12:13]
	global_load_dword v124, v[136:137], off nt
	v_lshl_add_u64 v[138:139], v[6:7], 0, s[12:13]
	global_load_dword v125, v[138:139], off nt
	v_lshl_add_u64 v[136:137], v[4:5], 0, s[12:13]
	global_load_dword v126, v[136:137], off nt
	v_lshl_add_u64 v[138:139], v[2:3], 0, s[12:13]
	global_load_dword v127, v[138:139], off nt
	s_add_u32 s12, s12, 0x1000
	s_addc_u32 s13, s13, 0
	v_lshl_add_u64 v[136:137], v[44:45], 0, s[12:13]
	global_load_dword v128, v[136:137], off nt
	v_lshl_add_u64 v[138:139], v[42:43], 0, s[12:13]
	global_load_dword v129, v[138:139], off nt
	v_lshl_add_u64 v[136:137], v[40:41], 0, s[12:13]
	global_load_dword v130, v[136:137], off nt
	v_lshl_add_u64 v[138:139], v[38:39], 0, s[12:13]
	global_load_dword v131, v[138:139], off nt
	v_lshl_add_u64 v[136:137], v[8:9], 0, s[12:13]
	global_load_dword v132, v[136:137], off nt
	v_lshl_add_u64 v[138:139], v[6:7], 0, s[12:13]
	global_load_dword v133, v[138:139], off nt
	v_lshl_add_u64 v[136:137], v[4:5], 0, s[12:13]
	global_load_dword v134, v[136:137], off nt
	v_lshl_add_u64 v[138:139], v[2:3], 0, s[12:13]
	global_load_dword v135, v[138:139], off nt
	s_add_u32 s12, s12, 0x1000
	s_addc_u32 s13, s13, 0
	v_lshl_add_u64 v[46:47], v[44:45], 0, s[12:13]
	v_lshl_add_u64 v[48:49], v[42:43], 0, s[12:13]
	v_lshl_add_u64 v[50:51], v[40:41], 0, s[12:13]
	v_lshl_add_u64 v[94:95], v[38:39], 0, s[12:13]
	v_lshl_add_u64 v[96:97], v[8:9], 0, s[12:13]
	v_lshl_add_u64 v[98:99], v[6:7], 0, s[12:13]
	v_lshl_add_u64 v[100:101], v[4:5], 0, s[12:13]
	v_lshl_add_u64 v[102:103], v[2:3], 0, s[12:13]
	global_load_dword v46, v[46:47], off nt
	s_nop 0
	global_load_dword v47, v[48:49], off nt
	s_nop 0
	global_load_dword v48, v[50:51], off nt
	global_load_dword v49, v[94:95], off nt
	s_nop 0
	global_load_dword v50, v[96:97], off nt
	global_load_dword v51, v[98:99], off nt
	global_load_dword v94, v[100:101], off nt
	global_load_dword v95, v[102:103], off nt
	s_add_u32 s12, s12, 0x1000
	s_addc_u32 s13, s13, 0
	v_add_u32_e32 v96, 0x400, v0
	s_waitcnt vmcnt(30)
	ds_write2_b32 v0, v112, v113 offset1:66
	s_waitcnt vmcnt(28)
	ds_write2_b32 v0, v114, v115 offset0:132 offset1:198
	s_waitcnt vmcnt(26)
	ds_write2_b32 v96, v116, v117 offset0:8 offset1:74
	s_waitcnt vmcnt(24)
	ds_write2_b32 v96, v118, v119 offset0:140 offset1:206
	v_add_u32_e32 v0, 0x840, v0
	v_add_u32_e32 v96, 0x400, v0
	s_waitcnt vmcnt(22)
	ds_write2_b32 v0, v120, v121 offset1:66
	s_waitcnt vmcnt(20)
	ds_write2_b32 v0, v122, v123 offset0:132 offset1:198
	s_waitcnt vmcnt(18)
	ds_write2_b32 v96, v124, v125 offset0:8 offset1:74
	s_waitcnt vmcnt(16)
	ds_write2_b32 v96, v126, v127 offset0:140 offset1:206
	v_add_u32_e32 v0, 0x840, v0
	v_add_u32_e32 v96, 0x400, v0
	s_waitcnt vmcnt(14)
	ds_write2_b32 v0, v128, v129 offset1:66
	s_waitcnt vmcnt(12)
	ds_write2_b32 v0, v130, v131 offset0:132 offset1:198
	s_waitcnt vmcnt(10)
	ds_write2_b32 v96, v132, v133 offset0:8 offset1:74
	s_waitcnt vmcnt(8)
	ds_write2_b32 v96, v134, v135 offset0:140 offset1:206
	v_add_u32_e32 v0, 0x840, v0
	v_add_u32_e32 v96, 0x400, v0
	s_waitcnt vmcnt(6)
	ds_write2_b32 v0, v46, v47 offset1:66
	s_waitcnt vmcnt(4)
	ds_write2_b32 v0, v48, v49 offset0:132 offset1:198
	s_waitcnt vmcnt(2)
	ds_write2_b32 v96, v50, v51 offset0:8 offset1:74
	s_waitcnt vmcnt(0)
	ds_write2_b32 v96, v94, v95 offset0:140 offset1:206
	v_add_u32_e32 v0, 0x840, v0
	s_waitcnt lgkmcnt(0)
	v_lshlrev_b32_e32 v39, 5, v93
	v_and_b32_e32 v0, 32, v93
	v_and_b32_e32 v38, 0x3c0, v39
	v_cmp_ne_u32_e32 vcc, 0, v0
	v_mov_b32_e32 v6, 1.0
	v_mov_b32_e32 v7, 1.0
	v_mov_b32_e32 v8, 1.0
	v_mov_b32_e32 v9, 1.0
	v_mov_b32_e32 v2, 1.0
	v_mov_b32_e32 v3, 1.0
	v_mov_b32_e32 v4, 1.0
	v_mov_b32_e32 v5, 1.0
	s_and_saveexec_b64 s[12:13], vcc
	s_cbranch_execz .LBB0_849
	v_lshlrev_b32_e32 v0, 2, v38
	v_lshl_add_u64 v[6:7], v[34:35], 0, v[0:1]
	global_load_dwordx4 v[2:5], v[6:7], off offset:16
	s_nop 0
	global_load_dwordx4 v[6:9], v[6:7], off
	s_andn2_b64 vcc, exec, s[18:19]
	s_cbranch_vccnz .LBB0_849
	v_lshl_add_u64 v[44:45], v[30:31], 0, v[0:1]
	global_load_dwordx4 v[40:43], v[44:45], off
	s_nop 0
	global_load_dwordx4 v[44:47], v[44:45], off offset:16
	s_waitcnt vmcnt(1)
	v_sub_f32_e32 v6, v6, v40
	v_sub_f32_e32 v7, v7, v41
	v_sub_f32_e32 v8, v8, v42
	v_sub_f32_e32 v9, v9, v43
	s_waitcnt vmcnt(0)
	v_sub_f32_e32 v2, v2, v44
	v_sub_f32_e32 v3, v3, v45
	v_sub_f32_e32 v4, v4, v46
	v_sub_f32_e32 v5, v5, v47

; __device__ __forceinline__ void tr_item(const float* W, int N, int Klim, int k0, int n0, bf16* WT, int ldk, int drow, int dcol, const float* sc, float* scr, int lane, const float* sc2 = nullptr, bool nts = true) {
;     if (k0 + 64 <= Klim) {
; #pragma unroll 8
;         for (int i = 0; i < 32; ++i) { const int kk = 2 * i + (lane >> 5); scr[kk * 33 + (lane & 31)] = __builtin_nontemporal_load(W + (size_t)(k0 + kk) * N + n0 + (lane & 31)); }
;     } else {
; #pragma unroll 8
;         for (int i = 0; i < 32; ++i) { const int kk = 2 * i + (lane >> 5); const int k = k0 + kk; float v = 0.f; if (k < Klim) v = W[(size_t)k * N + n0 + (lane & 31)]; scr[kk * 33 + (lane & 31)] = v; }
;     }
;     asm volatile("s_waitcnt lgkmcnt(0)" ::: "memory");
;     const int c = lane & 7;
;     f32x4_t sa = (f32x4_t){1.f, 1.f, 1.f, 1.f}, sb = sa;
;     if (sc) { sa = *(const f32x4_t*)(sc + k0 + 8 * c); sb = *(const f32x4_t*)(sc + k0 + 8 * c + 4);
;         if (sc2) { sa = sa - *(const f32x4_t*)(sc2 + k0 + 8 * c); sb = sb - *(const f32x4_t*)(sc2 + k0 + 8 * c + 4); } }
.LBB0_853:
	v_lshl_add_u64 v[136:137], v[44:45], 0, s[12:13]
	global_load_dword v112, v[136:137], off nt
	v_lshl_add_u64 v[138:139], v[42:43], 0, s[12:13]
	global_load_dword v113, v[138:139], off nt
	v_lshl_add_u64 v[136:137], v[40:41], 0, s[12:13]
	global_load_dword v114, v[136:137], off nt
	v_lshl_add_u64 v[138:139], v[38:39], 0, s[12:13]
	global_load_dword v115, v[138:139], off nt
	v_lshl_add_u64 v[136:137], v[8:9], 0, s[12:13]
	global_load_dword v116, v[136:137], off nt
	v_lshl_add_u64 v[138:139], v[6:7], 0, s[12:13]
	global_load_dword v117, v[138:139], off nt
	v_lshl_add_u64 v[136:137], v[4:5], 0, s[12:13]
	global_load_dword v118, v[136:137], off nt
	v_lshl_add_u64 v[138:139], v[2:3], 0, s[12:13]
	global_load_dword v119, v[138:139], off nt
	s_add_u32 s12, s12, 0x1000
	s_addc_u32 s13, s13, 0
	v_lshl_add_u64 v[136:137], v[44:45], 0, s[12:13]
	global_load_dword v120, v[136:137], off nt
	v_lshl_add_u64 v[138:139], v[42:43], 0, s[12:13]
	global_load_dword v121, v[138:139], off nt
	v_lshl_add_u64 v[136:137], v[40:41], 0, s[12:13]
	global_load_dword v122, v[136:137], off nt
	v_lshl_add_u64 v[138:139], v[38:39], 0, s[12:13]
	global_load_dword v123, v[138:139], off nt
	v_lshl_add_u64 v[136:137], v[8:9], 0, s[12:13]
	global_load_dword v124, v[136:137], off nt
	v_lshl_add_u64 v[138:139], v[6:7], 0, s[12:13]
	global_load_dword v125, v[138:139], off nt
	v_lshl_add_u64 v[136:137], v[4:5], 0, s[12:13]
	global_load_dword v126, v[136:137], off nt
	v_lshl_add_u64 v[138:139], v[2:3], 0, s[12:13]
	global_load_dword v127, v[138:139], off nt
	s_add_u32 s12, s12, 0x1000
	s_addc_u32 s13, s13, 0
	v_lshl_add_u64 v[136:137], v[44:45], 0, s[12:13]
	global_load_dword v128, v[136:137], off nt
	v_lshl_add_u64 v[138:139], v[42:43], 0, s[12:13]
	global_load_dword v129, v[138:139], off nt
	v_lshl_add_u64 v[136:137], v[40:41], 0, s[12:13]
	global_load_dword v130, v[136:137], off nt
	v_lshl_add_u64 v[138:139], v[38:39], 0, s[12:13]
	global_load_dword v131, v[138:139], off nt
	v_lshl_add_u64 v[136:137], v[8:9], 0, s[12:13]
	global_load_dword v132, v[136:137], off nt
	v_lshl_add_u64 v[138:139], v[6:7], 0, s[12:13]
	global_load_dword v133, v[138:139], off nt
	v_lshl_add_u64 v[136:137], v[4:5], 0, s[12:13]
	global_load_dword v134, v[136:137], off nt
	v_lshl_add_u64 v[138:139], v[2:3], 0, s[12:13]
	global_load_dword v135, v[138:139], off nt
	s_add_u32 s12, s12, 0x1000
	s_addc_u32 s13, s13, 0
	v_lshl_add_u64 v[46:47], v[44:45], 0, s[12:13]
	v_lshl_add_u64 v[48:49], v[42:43], 0, s[12:13]
	v_lshl_add_u64 v[50:51], v[40:41], 0, s[12:13]
	v_lshl_add_u64 v[94:95], v[38:39], 0, s[12:13]
	v_lshl_add_u64 v[96:97], v[8:9], 0, s[12:13]
	v_lshl_add_u64 v[98:99], v[6:7], 0, s[12:13]
	v_lshl_add_u64 v[100:101], v[4:5], 0, s[12:13]
	v_lshl_add_u64 v[102:103], v[2:3], 0, s[12:13]
	global_load_dword v46, v[46:47], off nt
	s_nop 0
	global_load_dword v47, v[48:49], off nt
	s_nop 0
	global_load_dword v48, v[50:51], off nt
	global_load_dword v49, v[94:95], off nt
	s_nop 0
	global_load_dword v50, v[96:97], off nt
	global_load_dword v51, v[98:99], off nt
	global_load_dword v94, v[100:101], off nt
	global_load_dword v95, v[102:103], off nt
	s_add_u32 s12, s12, 0x1000
	s_addc_u32 s13, s13, 0
	v_add_u32_e32 v96, 0x400, v0
	s_waitcnt vmcnt(30)
	ds_write2_b32 v0, v112, v113 offset1:66
	s_waitcnt vmcnt(28)
	ds_write2_b32 v0, v114, v115 offset0:132 offset1:198
	s_waitcnt vmcnt(26)
	ds_write2_b32 v96, v116, v117 offset0:8 offset1:74
	s_waitcnt vmcnt(24)
	ds_write2_b32 v96, v118, v119 offset0:140 offset1:206
	v_add_u32_e32 v0, 0x840, v0
	v_add_u32_e32 v96, 0x400, v0
	s_waitcnt vmcnt(22)
	ds_write2_b32 v0, v120, v121 offset1:66
	s_waitcnt vmcnt(20)
	ds_write2_b32 v0, v122, v123 offset0:132 offset1:198
	s_waitcnt vmcnt(18)
	ds_write2_b32 v96, v124, v125 offset0:8 offset1:74
	s_waitcnt vmcnt(16)
	ds_write2_b32 v96, v126, v127 offset0:140 offset1:206
	v_add_u32_e32 v0, 0x840, v0
	v_add_u32_e32 v96, 0x400, v0
	s_waitcnt vmcnt(14)
	ds_write2_b32 v0, v128, v129 offset1:66
	s_waitcnt vmcnt(12)
	ds_write2_b32 v0, v130, v131 offset0:132 offset1:198
	s_waitcnt vmcnt(10)
	ds_write2_b32 v96, v132, v133 offset0:8 offset1:74
	s_waitcnt vmcnt(8)
	ds_write2_b32 v96, v134, v135 offset0:140 offset1:206
	v_add_u32_e32 v0, 0x840, v0
	v_add_u32_e32 v96, 0x400, v0
	s_waitcnt vmcnt(6)
	ds_write2_b32 v0, v46, v47 offset1:66
	s_waitcnt vmcnt(4)
	ds_write2_b32 v0, v48, v49 offset0:132 offset1:198
	s_waitcnt vmcnt(2)
	ds_write2_b32 v96, v50, v51 offset0:8 offset1:74
	s_waitcnt vmcnt(0)
	ds_write2_b32 v96, v94, v95 offset0:140 offset1:206
	v_add_u32_e32 v0, 0x840, v0
	s_waitcnt lgkmcnt(0)
	v_lshlrev_b32_e32 v39, 5, v93
	v_and_b32_e32 v0, 32, v93
	v_and_b32_e32 v38, 0x3c0, v39
	v_cmp_ne_u32_e32 vcc, 0, v0
	v_mov_b32_e32 v6, 1.0
	v_mov_b32_e32 v7, 1.0
	v_mov_b32_e32 v8, 1.0
	v_mov_b32_e32 v9, 1.0
	v_mov_b32_e32 v2, 1.0
	v_mov_b32_e32 v3, 1.0
	v_mov_b32_e32 v4, 1.0
	v_mov_b32_e32 v5, 1.0
	s_and_saveexec_b64 s[12:13], vcc
	s_cbranch_execz .LBB0_857
	v_lshlrev_b32_e32 v0, 2, v38
	v_lshl_add_u64 v[6:7], v[36:37], 0, v[0:1]
	global_load_dwordx4 v[2:5], v[6:7], off offset:16
	s_nop 0
	global_load_dwordx4 v[6:9], v[6:7], off
	s_andn2_b64 vcc, exec, s[18:19]
	s_cbranch_vccnz .LBB0_857
	v_lshl_add_u64 v[44:45], v[30:31], 0, v[0:1]
	global_load_dwordx4 v[40:43], v[44:45], off
	s_nop 0
	global_load_dwordx4 v[44:47], v[44:45], off offset:16
	s_waitcnt vmcnt(1)
	v_sub_f32_e32 v6, v6, v40
	v_sub_f32_e32 v7, v7, v41
	v_sub_f32_e32 v8, v8, v42
	v_sub_f32_e32 v9, v9, v43
	s_waitcnt vmcnt(0)
	v_sub_f32_e32 v2, v2, v44
	v_sub_f32_e32 v3, v3, v45
	v_sub_f32_e32 v4, v4, v46
	v_sub_f32_e32 v5, v5, v47

; __device__ __forceinline__ unsigned pk2(float lo, float hi) { const f32x2_cv v = {lo, hi}; const bf16x2_cv b = __builtin_convertvector(v, bf16x2_cv); return __builtin_bit_cast(unsigned, b); }
; __device__ __forceinline__ void tr_item(const float* W, int N, int Klim, int k0, int n0, bf16* WT, int ldk, int drow, int dcol, const float* sc, float* scr, int lane, const float* sc2 = nullptr, bool nts = true) {
;     if (k0 + 64 <= Klim) {
; #pragma unroll 8
;         for (int i = 0; i < 32; ++i) { const int kk = 2 * i + (lane >> 5); scr[kk * 33 + (lane & 31)] = __builtin_nontemporal_load(W + (size_t)(k0 + kk) * N + n0 + (lane & 31)); }
;     } else {
; #pragma unroll 8
;         for (int i = 0; i < 32; ++i) { const int kk = 2 * i + (lane >> 5); const int k = k0 + kk; float v = 0.f; if (k < Klim) v = W[(size_t)k * N + n0 + (lane & 31)]; scr[kk * 33 + (lane & 31)] = v; }
;     }
;     asm volatile("s_waitcnt lgkmcnt(0)" ::: "memory");
;     const int c = lane & 7;
;     f32x4_t sa = (f32x4_t){1.f, 1.f, 1.f, 1.f}, sb = sa;
;     if (sc) { sa = *(const f32x4_t*)(sc + k0 + 8 * c); sb = *(const f32x4_t*)(sc + k0 + 8 * c + 4);
;         if (sc2) { sa = sa - *(const f32x4_t*)(sc2 + k0 + 8 * c); sb = sb - *(const f32x4_t*)(sc2 + k0 + 8 * c + 4); } }
; #pragma unroll
;     for (int j = 0; j < 4; ++j) { const int n = (lane >> 3) + 8 * j; const float* s = scr + (8 * c) * 33 + n;
;         u32x4_t o; o.x = pk2(s[0 * 33] * sa[0], s[1 * 33] * sa[1]); o.y = pk2(s[2 * 33] * sa[2], s[3 * 33] * sa[3]); o.z = pk2(s[4 * 33] * sb[0], s[5 * 33] * sb[1]); o.w = pk2(s[6 * 33] * sb[2], s[7 * 33] * sb[3]);
;         if (nts) __builtin_nontemporal_store(o, (u32x4_t*)(WT + (size_t)(drow + n) * ldk + dcol + k0 + 8 * c)); else *(u32x4_t*)(WT + (size_t)(drow + n) * ldk + dcol + k0 + 8 * c) = o; }
.LBB0_861:
	v_lshl_add_u64 v[136:137], v[44:45], 0, s[12:13]
	global_load_dword v112, v[136:137], off nt
	v_lshl_add_u64 v[138:139], v[42:43], 0, s[12:13]
	global_load_dword v113, v[138:139], off nt
	v_lshl_add_u64 v[136:137], v[40:41], 0, s[12:13]
	global_load_dword v114, v[136:137], off nt
	v_lshl_add_u64 v[138:139], v[38:39], 0, s[12:13]
	global_load_dword v115, v[138:139], off nt
	v_lshl_add_u64 v[136:137], v[8:9], 0, s[12:13]
	global_load_dword v116, v[136:137], off nt
	v_lshl_add_u64 v[138:139], v[6:7], 0, s[12:13]
	global_load_dword v117, v[138:139], off nt
	v_lshl_add_u64 v[136:137], v[4:5], 0, s[12:13]
	global_load_dword v118, v[136:137], off nt
	v_lshl_add_u64 v[138:139], v[2:3], 0, s[12:13]
	global_load_dword v119, v[138:139], off nt
	s_add_u32 s12, s12, 0x10000
	s_addc_u32 s13, s13, 0
	v_lshl_add_u64 v[136:137], v[44:45], 0, s[12:13]
	global_load_dword v120, v[136:137], off nt
	v_lshl_add_u64 v[138:139], v[42:43], 0, s[12:13]
	global_load_dword v121, v[138:139], off nt
	v_lshl_add_u64 v[136:137], v[40:41], 0, s[12:13]
	global_load_dword v122, v[136:137], off nt
	v_lshl_add_u64 v[138:139], v[38:39], 0, s[12:13]
	global_load_dword v123, v[138:139], off nt
	v_lshl_add_u64 v[136:137], v[8:9], 0, s[12:13]
	global_load_dword v124, v[136:137], off nt
	v_lshl_add_u64 v[138:139], v[6:7], 0, s[12:13]
	global_load_dword v125, v[138:139], off nt
	v_lshl_add_u64 v[136:137], v[4:5], 0, s[12:13]
	global_load_dword v126, v[136:137], off nt
	v_lshl_add_u64 v[138:139], v[2:3], 0, s[12:13]
	global_load_dword v127, v[138:139], off nt
	s_add_u32 s12, s12, 0x10000
	s_addc_u32 s13, s13, 0
	v_lshl_add_u64 v[136:137], v[44:45], 0, s[12:13]
	global_load_dword v128, v[136:137], off nt
	v_lshl_add_u64 v[138:139], v[42:43], 0, s[12:13]
	global_load_dword v129, v[138:139], off nt
	v_lshl_add_u64 v[136:137], v[40:41], 0, s[12:13]
	global_load_dword v130, v[136:137], off nt
	v_lshl_add_u64 v[138:139], v[38:39], 0, s[12:13]
	global_load_dword v131, v[138:139], off nt
	v_lshl_add_u64 v[136:137], v[8:9], 0, s[12:13]
	global_load_dword v132, v[136:137], off nt
	v_lshl_add_u64 v[138:139], v[6:7], 0, s[12:13]
	global_load_dword v133, v[138:139], off nt
	v_lshl_add_u64 v[136:137], v[4:5], 0, s[12:13]
	global_load_dword v134, v[136:137], off nt
	v_lshl_add_u64 v[138:139], v[2:3], 0, s[12:13]
	global_load_dword v135, v[138:139], off nt
	s_add_u32 s12, s12, 0x10000
	s_addc_u32 s13, s13, 0
	v_lshl_add_u64 v[48:49], v[44:45], 0, s[12:13]
	v_lshl_add_u64 v[50:51], v[42:43], 0, s[12:13]
	v_lshl_add_u64 v[94:95], v[40:41], 0, s[12:13]
	v_lshl_add_u64 v[96:97], v[38:39], 0, s[12:13]
	v_lshl_add_u64 v[98:99], v[8:9], 0, s[12:13]
	v_lshl_add_u64 v[100:101], v[6:7], 0, s[12:13]
	v_lshl_add_u64 v[102:103], v[4:5], 0, s[12:13]
	v_lshl_add_u64 v[104:105], v[2:3], 0, s[12:13]
	global_load_dword v48, v[48:49], off nt
	s_nop 0
	global_load_dword v49, v[50:51], off nt
	s_nop 0
	global_load_dword v50, v[94:95], off nt
	global_load_dword v51, v[96:97], off nt
	s_nop 0
	global_load_dword v94, v[98:99], off nt
	global_load_dword v95, v[100:101], off nt
	global_load_dword v96, v[102:103], off nt
	global_load_dword v97, v[104:105], off nt
	s_add_u32 s12, s12, 0x10000
	s_addc_u32 s13, s13, 0
	v_add_u32_e32 v98, 0x400, v0
	s_waitcnt vmcnt(30)
	ds_write2_b32 v0, v112, v113 offset1:66
	s_waitcnt vmcnt(28)
	ds_write2_b32 v0, v114, v115 offset0:132 offset1:198
	s_waitcnt vmcnt(26)
	ds_write2_b32 v98, v116, v117 offset0:8 offset1:74
	s_waitcnt vmcnt(24)
	ds_write2_b32 v98, v118, v119 offset0:140 offset1:206
	v_add_u32_e32 v0, 0x840, v0
	v_add_u32_e32 v98, 0x400, v0
	s_waitcnt vmcnt(22)
	ds_write2_b32 v0, v120, v121 offset1:66
	s_waitcnt vmcnt(20)
	ds_write2_b32 v0, v122, v123 offset0:132 offset1:198
	s_waitcnt vmcnt(18)
	ds_write2_b32 v98, v124, v125 offset0:8 offset1:74
	s_waitcnt vmcnt(16)
	ds_write2_b32 v98, v126, v127 offset0:140 offset1:206
	v_add_u32_e32 v0, 0x840, v0
	v_add_u32_e32 v98, 0x400, v0
	s_waitcnt vmcnt(14)
	ds_write2_b32 v0, v128, v129 offset1:66
	s_waitcnt vmcnt(12)
	ds_write2_b32 v0, v130, v131 offset0:132 offset1:198
	s_waitcnt vmcnt(10)
	ds_write2_b32 v98, v132, v133 offset0:8 offset1:74
	s_waitcnt vmcnt(8)
	ds_write2_b32 v98, v134, v135 offset0:140 offset1:206
	v_add_u32_e32 v0, 0x840, v0
	v_add_u32_e32 v98, 0x400, v0
	s_waitcnt vmcnt(6)
	ds_write2_b32 v0, v48, v49 offset1:66
	s_waitcnt vmcnt(4)
	ds_write2_b32 v0, v50, v51 offset0:132 offset1:198
	s_waitcnt vmcnt(2)
	ds_write2_b32 v98, v94, v95 offset0:8 offset1:74
	s_waitcnt vmcnt(0)
	ds_write2_b32 v98, v96, v97 offset0:140 offset1:206
	v_add_u32_e32 v0, 0x840, v0
	v_lshlrev_b32_e32 v0, 5, v93
	v_and_b32_e32 v0, 0x3e0, v0
	s_waitcnt lgkmcnt(0)
	v_lshl_or_b32 v96, v47, 10, v0
	v_lshlrev_b32_e32 v0, 2, v46
	ds_read2_b32 v[6:7], v52 offset0:33 offset1:41
	ds_read2_b32 v[8:9], v52 offset1:8
	ds_read2_b32 v[38:39], v52 offset0:66 offset1:74
	ds_read2_b32 v[40:41], v52 offset0:99 offset1:107
	ds_read2_b32 v[42:43], v52 offset0:132 offset1:140
	ds_read2_b32 v[44:45], v52 offset0:165 offset1:173
	ds_read2_b32 v[46:47], v52 offset0:198 offset1:206
	ds_read2_b32 v[48:49], v52 offset0:231 offset1:239
	v_and_b32_e32 v0, 0x780, v0
	v_lshl_add_u64 v[50:51], v[20:21], 0, v[0:1]
	v_or_b32_e32 v0, v96, v29
	v_lshlrev_b64 v[94:95], 11, v[0:1]
	s_waitcnt lgkmcnt(6)
	v_cvt_pk_bf16_f32 v2, v8, v6
	s_waitcnt lgkmcnt(4)
	v_cvt_pk_bf16_f32 v3, v38, v40
	s_waitcnt lgkmcnt(2)
	v_cvt_pk_bf16_f32 v4, v42, v44
	s_waitcnt lgkmcnt(0)
	v_cvt_pk_bf16_f32 v5, v46, v48
	v_lshl_add_u64 v[94:95], v[50:51], 0, v[94:95]
	global_store_dwordx4 v[94:95], v[2:5], off
	v_or_b32_e32 v0, v96, v53
	s_nop 0
	v_cvt_pk_bf16_f32 v2, v9, v7
	v_cvt_pk_bf16_f32 v3, v39, v41
	v_cvt_pk_bf16_f32 v4, v43, v45
	v_cvt_pk_bf16_f32 v5, v47, v49
	ds_read2_b32 v[8:9], v52 offset0:49 offset1:57
	ds_read2_b32 v[38:39], v52 offset0:16 offset1:24
	ds_read2_b32 v[40:41], v52 offset0:82 offset1:90
	ds_read2_b32 v[42:43], v52 offset0:115 offset1:123
	ds_read2_b32 v[44:45], v52 offset0:148 offset1:156
	ds_read2_b32 v[46:47], v52 offset0:181 offset1:189
	ds_read2_b32 v[48:49], v52 offset0:214 offset1:222
	ds_read2_b32 v[94:95], v52 offset0:247 offset1:255
	v_lshlrev_b64 v[6:7], 11, v[0:1]
	v_lshl_add_u64 v[6:7], v[50:51], 0, v[6:7]
	v_or_b32_e32 v0, v96, v54
	global_store_dwordx4 v[6:7], v[2:5], off
	v_lshlrev_b64 v[6:7], 11, v[0:1]
	v_lshl_add_u64 v[6:7], v[50:51], 0, v[6:7]
	s_waitcnt lgkmcnt(6)
	v_cvt_pk_bf16_f32 v2, v38, v8
	s_waitcnt lgkmcnt(4)
	v_cvt_pk_bf16_f32 v3, v40, v42
	s_waitcnt lgkmcnt(2)
	v_cvt_pk_bf16_f32 v4, v44, v46
	s_waitcnt lgkmcnt(0)
	v_cvt_pk_bf16_f32 v5, v48, v94
	v_or_b32_e32 v0, v96, v55
	global_store_dwordx4 v[6:7], v[2:5], off
	v_lshlrev_b64 v[6:7], 11, v[0:1]
	v_lshl_add_u64 v[6:7], v[50:51], 0, v[6:7]
	v_cvt_pk_bf16_f32 v2, v39, v9
	v_cvt_pk_bf16_f32 v3, v41, v43
	v_cvt_pk_bf16_f32 v4, v45, v47
	v_cvt_pk_bf16_f32 v5, v49, v95
	global_store_dwordx4 v[6:7], v[2:5], off
	s_waitcnt lgkmcnt(0)

; __device__ __forceinline__ void tr_item(const float* W, int N, int Klim, int k0, int n0, bf16* WT, int ldk, int drow, int dcol, const float* sc, float* scr, int lane, const float* sc2 = nullptr, bool nts = true) {
;     if (k0 + 64 <= Klim) {
; #pragma unroll 8
;         for (int i = 0; i < 32; ++i) { const int kk = 2 * i + (lane >> 5); scr[kk * 33 + (lane & 31)] = __builtin_nontemporal_load(W + (size_t)(k0 + kk) * N + n0 + (lane & 31)); }
.LBB0_867:
	v_lshl_add_u64 v[136:137], v[50:51], 0, s[42:43]
	global_load_dword v112, v[136:137], off nt
	v_lshl_add_u64 v[138:139], v[48:49], 0, s[42:43]
	global_load_dword v113, v[138:139], off nt
	v_lshl_add_u64 v[136:137], v[46:47], 0, s[42:43]
	global_load_dword v114, v[136:137], off nt
	v_lshl_add_u64 v[138:139], v[44:45], 0, s[42:43]
	global_load_dword v115, v[138:139], off nt
	v_lshl_add_u64 v[136:137], v[42:43], 0, s[42:43]
	global_load_dword v116, v[136:137], off nt
	v_lshl_add_u64 v[138:139], v[40:41], 0, s[42:43]
	global_load_dword v117, v[138:139], off nt
	v_lshl_add_u64 v[136:137], v[38:39], 0, s[42:43]
	global_load_dword v118, v[136:137], off nt
	v_lshl_add_u64 v[138:139], v[8:9], 0, s[42:43]
	global_load_dword v119, v[138:139], off nt
	s_add_u32 s42, s42, 0x10000
	s_addc_u32 s43, s43, 0
	v_lshl_add_u64 v[136:137], v[50:51], 0, s[42:43]
	global_load_dword v120, v[136:137], off nt
	v_lshl_add_u64 v[138:139], v[48:49], 0, s[42:43]
	global_load_dword v121, v[138:139], off nt
	v_lshl_add_u64 v[136:137], v[46:47], 0, s[42:43]
	global_load_dword v122, v[136:137], off nt
	v_lshl_add_u64 v[138:139], v[44:45], 0, s[42:43]
	global_load_dword v123, v[138:139], off nt
	v_lshl_add_u64 v[136:137], v[42:43], 0, s[42:43]
	global_load_dword v124, v[136:137], off nt
	v_lshl_add_u64 v[138:139], v[40:41], 0, s[42:43]
	global_load_dword v125, v[138:139], off nt
	v_lshl_add_u64 v[136:137], v[38:39], 0, s[42:43]
	global_load_dword v126, v[136:137], off nt
	v_lshl_add_u64 v[138:139], v[8:9], 0, s[42:43]
	global_load_dword v127, v[138:139], off nt
	s_add_u32 s42, s42, 0x10000
	s_addc_u32 s43, s43, 0
	v_lshl_add_u64 v[136:137], v[50:51], 0, s[42:43]
	global_load_dword v128, v[136:137], off nt
	v_lshl_add_u64 v[138:139], v[48:49], 0, s[42:43]
	global_load_dword v129, v[138:139], off nt
	v_lshl_add_u64 v[136:137], v[46:47], 0, s[42:43]
	global_load_dword v130, v[136:137], off nt
	v_lshl_add_u64 v[138:139], v[44:45], 0, s[42:43]
	global_load_dword v131, v[138:139], off nt
	v_lshl_add_u64 v[136:137], v[42:43], 0, s[42:43]
	global_load_dword v132, v[136:137], off nt
	v_lshl_add_u64 v[138:139], v[40:41], 0, s[42:43]
	global_load_dword v133, v[138:139], off nt
	v_lshl_add_u64 v[136:137], v[38:39], 0, s[42:43]
	global_load_dword v134, v[136:137], off nt
	v_lshl_add_u64 v[138:139], v[8:9], 0, s[42:43]
	global_load_dword v135, v[138:139], off nt
	s_add_u32 s42, s42, 0x10000
	s_addc_u32 s43, s43, 0
	v_lshl_add_u64 v[6:7], v[50:51], 0, s[42:43]
	v_lshl_add_u64 v[94:95], v[48:49], 0, s[42:43]
	v_lshl_add_u64 v[96:97], v[46:47], 0, s[42:43]
	v_lshl_add_u64 v[98:99], v[44:45], 0, s[42:43]
	v_lshl_add_u64 v[100:101], v[42:43], 0, s[42:43]
	v_lshl_add_u64 v[102:103], v[40:41], 0, s[42:43]
	v_lshl_add_u64 v[104:105], v[38:39], 0, s[42:43]
	v_lshl_add_u64 v[106:107], v[8:9], 0, s[42:43]
	global_load_dword v3, v[6:7], off nt
	s_nop 0
	global_load_dword v7, v[94:95], off nt
	s_nop 0
	global_load_dword v94, v[96:97], off nt
	global_load_dword v95, v[98:99], off nt
	s_nop 0
	global_load_dword v96, v[100:101], off nt
	global_load_dword v97, v[102:103], off nt
	global_load_dword v98, v[104:105], off nt
	global_load_dword v99, v[106:107], off nt
	s_add_u32 s42, s42, 0x10000
	s_addc_u32 s43, s43, 0
	v_add_u32_e32 v100, 0x400, v0
	s_waitcnt vmcnt(30)
	ds_write2_b32 v0, v112, v113 offset1:66
	s_waitcnt vmcnt(28)
	ds_write2_b32 v0, v114, v115 offset0:132 offset1:198
	s_waitcnt vmcnt(26)
	ds_write2_b32 v100, v116, v117 offset0:8 offset1:74
	s_waitcnt vmcnt(24)
	ds_write2_b32 v100, v118, v119 offset0:140 offset1:206
	v_add_u32_e32 v0, 0x840, v0
	v_add_u32_e32 v100, 0x400, v0
	s_waitcnt vmcnt(22)
	ds_write2_b32 v0, v120, v121 offset1:66
	s_waitcnt vmcnt(20)
	ds_write2_b32 v0, v122, v123 offset0:132 offset1:198
	s_waitcnt vmcnt(18)
	ds_write2_b32 v100, v124, v125 offset0:8 offset1:74
	s_waitcnt vmcnt(16)
	ds_write2_b32 v100, v126, v127 offset0:140 offset1:206
	v_add_u32_e32 v0, 0x840, v0
	v_add_u32_e32 v100, 0x400, v0
	s_waitcnt vmcnt(14)
	ds_write2_b32 v0, v128, v129 offset1:66
	s_waitcnt vmcnt(12)
	ds_write2_b32 v0, v130, v131 offset0:132 offset1:198
	s_waitcnt vmcnt(10)
	ds_write2_b32 v100, v132, v133 offset0:8 offset1:74
	s_waitcnt vmcnt(8)
	ds_write2_b32 v100, v134, v135 offset0:140 offset1:206
	v_add_u32_e32 v0, 0x840, v0
	v_add_u32_e32 v100, 0x400, v0
	s_waitcnt vmcnt(6)
	ds_write2_b32 v0, v3, v7 offset1:66
	s_waitcnt vmcnt(4)
	ds_write2_b32 v0, v94, v95 offset0:132 offset1:198
	s_waitcnt vmcnt(2)
	ds_write2_b32 v100, v96, v97 offset0:8 offset1:74
	s_waitcnt vmcnt(0)
	ds_write2_b32 v100, v98, v99 offset0:140 offset1:206
	v_add_u32_e32 v0, 0x840, v0

; __device__ __forceinline__ void tr_item(const float* W, int N, int Klim, int k0, int n0, bf16* WT, int ldk, int drow, int dcol, const float* sc, float* scr, int lane, const float* sc2 = nullptr, bool nts = true) {
;     if (k0 + 64 <= Klim) {
; #pragma unroll 8
;         for (int i = 0; i < 32; ++i) { const int kk = 2 * i + (lane >> 5); scr[kk * 33 + (lane & 31)] = __builtin_nontemporal_load(W + (size_t)(k0 + kk) * N + n0 + (lane & 31)); }
.LBB0_892:
	v_lshl_add_u64 v[136:137], v[50:51], 0, s[40:41]
	global_load_dword v112, v[136:137], off nt
	v_lshl_add_u64 v[138:139], v[48:49], 0, s[40:41]
	global_load_dword v113, v[138:139], off nt
	v_lshl_add_u64 v[136:137], v[46:47], 0, s[40:41]
	global_load_dword v114, v[136:137], off nt
	v_lshl_add_u64 v[138:139], v[44:45], 0, s[40:41]
	global_load_dword v115, v[138:139], off nt
	v_lshl_add_u64 v[136:137], v[42:43], 0, s[40:41]
	global_load_dword v116, v[136:137], off nt
	v_lshl_add_u64 v[138:139], v[6:7], 0, s[40:41]
	global_load_dword v117, v[138:139], off nt
	v_lshl_add_u64 v[136:137], v[4:5], 0, s[40:41]
	global_load_dword v118, v[136:137], off nt
	v_lshl_add_u64 v[138:139], v[2:3], 0, s[40:41]
	global_load_dword v119, v[138:139], off nt
	s_add_u32 s40, s40, 0x58000
	s_addc_u32 s41, s41, 0
	v_lshl_add_u64 v[136:137], v[50:51], 0, s[40:41]
	global_load_dword v120, v[136:137], off nt
	v_lshl_add_u64 v[138:139], v[48:49], 0, s[40:41]
	global_load_dword v121, v[138:139], off nt
	v_lshl_add_u64 v[136:137], v[46:47], 0, s[40:41]
	global_load_dword v122, v[136:137], off nt
	v_lshl_add_u64 v[138:139], v[44:45], 0, s[40:41]
	global_load_dword v123, v[138:139], off nt
	v_lshl_add_u64 v[136:137], v[42:43], 0, s[40:41]
	global_load_dword v124, v[136:137], off nt
	v_lshl_add_u64 v[138:139], v[6:7], 0, s[40:41]
	global_load_dword v125, v[138:139], off nt
	v_lshl_add_u64 v[136:137], v[4:5], 0, s[40:41]
	global_load_dword v126, v[136:137], off nt
	v_lshl_add_u64 v[138:139], v[2:3], 0, s[40:41]
	global_load_dword v127, v[138:139], off nt
	s_add_u32 s40, s40, 0x58000
	s_addc_u32 s41, s41, 0
	v_lshl_add_u64 v[136:137], v[50:51], 0, s[40:41]
	global_load_dword v128, v[136:137], off nt
	v_lshl_add_u64 v[138:139], v[48:49], 0, s[40:41]
	global_load_dword v129, v[138:139], off nt
	v_lshl_add_u64 v[136:137], v[46:47], 0, s[40:41]
	global_load_dword v130, v[136:137], off nt
	v_lshl_add_u64 v[138:139], v[44:45], 0, s[40:41]
	global_load_dword v131, v[138:139], off nt
	v_lshl_add_u64 v[136:137], v[42:43], 0, s[40:41]
	global_load_dword v132, v[136:137], off nt
	v_lshl_add_u64 v[138:139], v[6:7], 0, s[40:41]
	global_load_dword v133, v[138:139], off nt
	v_lshl_add_u64 v[136:137], v[4:5], 0, s[40:41]
	global_load_dword v134, v[136:137], off nt
	v_lshl_add_u64 v[138:139], v[2:3], 0, s[40:41]
	global_load_dword v135, v[138:139], off nt
	s_add_u32 s40, s40, 0x58000
	s_addc_u32 s41, s41, 0
	v_lshl_add_u64 v[8:9], v[50:51], 0, s[40:41]
	v_lshl_add_u64 v[98:99], v[48:49], 0, s[40:41]
	v_lshl_add_u64 v[100:101], v[46:47], 0, s[40:41]
	v_lshl_add_u64 v[102:103], v[44:45], 0, s[40:41]
	v_lshl_add_u64 v[104:105], v[42:43], 0, s[40:41]
	v_lshl_add_u64 v[106:107], v[6:7], 0, s[40:41]
	v_lshl_add_u64 v[108:109], v[4:5], 0, s[40:41]
	v_lshl_add_u64 v[110:111], v[2:3], 0, s[40:41]
	global_load_dword v41, v[8:9], off nt
	global_load_dword v97, v[98:99], off nt
	s_nop 0
	global_load_dword v98, v[100:101], off nt
	global_load_dword v99, v[102:103], off nt
	s_nop 0
	global_load_dword v100, v[104:105], off nt
	global_load_dword v101, v[106:107], off nt
	global_load_dword v102, v[108:109], off nt
	global_load_dword v103, v[110:111], off nt
	s_add_u32 s40, s40, 0x58000
	s_addc_u32 s41, s41, 0
	v_add_u32_e32 v104, 0x400, v0
	s_waitcnt vmcnt(30)
	ds_write2_b32 v0, v112, v113 offset1:66
	s_waitcnt vmcnt(28)
	ds_write2_b32 v0, v114, v115 offset0:132 offset1:198
	s_waitcnt vmcnt(26)
	ds_write2_b32 v104, v116, v117 offset0:8 offset1:74
	s_waitcnt vmcnt(24)
	ds_write2_b32 v104, v118, v119 offset0:140 offset1:206
	v_add_u32_e32 v0, 0x840, v0
	v_add_u32_e32 v104, 0x400, v0
	s_waitcnt vmcnt(22)
	ds_write2_b32 v0, v120, v121 offset1:66
	s_waitcnt vmcnt(20)
	ds_write2_b32 v0, v122, v123 offset0:132 offset1:198
	s_waitcnt vmcnt(18)
	ds_write2_b32 v104, v124, v125 offset0:8 offset1:74
	s_waitcnt vmcnt(16)
	ds_write2_b32 v104, v126, v127 offset0:140 offset1:206
	v_add_u32_e32 v0, 0x840, v0
	v_add_u32_e32 v104, 0x400, v0
	s_waitcnt vmcnt(14)
	ds_write2_b32 v0, v128, v129 offset1:66
	s_waitcnt vmcnt(12)
	ds_write2_b32 v0, v130, v131 offset0:132 offset1:198
	s_waitcnt vmcnt(10)
	ds_write2_b32 v104, v132, v133 offset0:8 offset1:74
	s_waitcnt vmcnt(8)
	ds_write2_b32 v104, v134, v135 offset0:140 offset1:206
	v_add_u32_e32 v0, 0x840, v0
	v_add_u32_e32 v104, 0x400, v0
	s_waitcnt vmcnt(6)
	ds_write2_b32 v0, v41, v97 offset1:66
	s_waitcnt vmcnt(4)
	ds_write2_b32 v0, v98, v99 offset0:132 offset1:198
	s_waitcnt vmcnt(2)
	ds_write2_b32 v104, v100, v101 offset0:8 offset1:74
	s_waitcnt vmcnt(0)
	ds_write2_b32 v104, v102, v103 offset0:140 offset1:206
	v_add_u32_e32 v0, 0x840, v0

; __device__ __forceinline__ unsigned pk2(float lo, float hi) { const f32x2_cv v = {lo, hi}; const bf16x2_cv b = __builtin_convertvector(v, bf16x2_cv); return __builtin_bit_cast(unsigned, b); }
; __device__ __forceinline__ void tr_item(const float* W, int N, int Klim, int k0, int n0, bf16* WT, int ldk, int drow, int dcol, const float* sc, float* scr, int lane, const float* sc2 = nullptr, bool nts = true) {
;     if (k0 + 64 <= Klim) {
; #pragma unroll 8
;         for (int i = 0; i < 32; ++i) { const int kk = 2 * i + (lane >> 5); scr[kk * 33 + (lane & 31)] = __builtin_nontemporal_load(W + (size_t)(k0 + kk) * N + n0 + (lane & 31)); }
;     } else {
; #pragma unroll 8
;         for (int i = 0; i < 32; ++i) { const int kk = 2 * i + (lane >> 5); const int k = k0 + kk; float v = 0.f; if (k < Klim) v = W[(size_t)k * N + n0 + (lane & 31)]; scr[kk * 33 + (lane & 31)] = v; }
;     }
;     asm volatile("s_waitcnt lgkmcnt(0)" ::: "memory");
;     const int c = lane & 7;
;     f32x4_t sa = (f32x4_t){1.f, 1.f, 1.f, 1.f}, sb = sa;
;     if (sc) { sa = *(const f32x4_t*)(sc + k0 + 8 * c); sb = *(const f32x4_t*)(sc + k0 + 8 * c + 4);
;         if (sc2) { sa = sa - *(const f32x4_t*)(sc2 + k0 + 8 * c); sb = sb - *(const f32x4_t*)(sc2 + k0 + 8 * c + 4); } }
; #pragma unroll
;     for (int j = 0; j < 4; ++j) { const int n = (lane >> 3) + 8 * j; const float* s = scr + (8 * c) * 33 + n;
;         u32x4_t o; o.x = pk2(s[0 * 33] * sa[0], s[1 * 33] * sa[1]); o.y = pk2(s[2 * 33] * sa[2], s[3 * 33] * sa[3]); o.z = pk2(s[4 * 33] * sb[0], s[5 * 33] * sb[1]); o.w = pk2(s[6 * 33] * sb[2], s[7 * 33] * sb[3]);
;         if (nts) __builtin_nontemporal_store(o, (u32x4_t*)(WT + (size_t)(drow + n) * ldk + dcol + k0 + 8 * c)); else *(u32x4_t*)(WT + (size_t)(drow + n) * ldk + dcol + k0 + 8 * c) = o; }
.LBB0_919:
	v_lshl_add_u64 v[136:137], v[44:45], 0, s[12:13]
	global_load_dword v112, v[136:137], off nt
	v_lshl_add_u64 v[138:139], v[42:43], 0, s[12:13]
	global_load_dword v113, v[138:139], off nt
	v_lshl_add_u64 v[136:137], v[40:41], 0, s[12:13]
	global_load_dword v114, v[136:137], off nt
	v_lshl_add_u64 v[138:139], v[38:39], 0, s[12:13]
	global_load_dword v115, v[138:139], off nt
	v_lshl_add_u64 v[136:137], v[8:9], 0, s[12:13]
	global_load_dword v116, v[136:137], off nt
	v_lshl_add_u64 v[138:139], v[6:7], 0, s[12:13]
	global_load_dword v117, v[138:139], off nt
	v_lshl_add_u64 v[136:137], v[4:5], 0, s[12:13]
	global_load_dword v118, v[136:137], off nt
	v_lshl_add_u64 v[138:139], v[2:3], 0, s[12:13]
	global_load_dword v119, v[138:139], off nt
	s_add_u32 s12, s12, 0x10000
	s_addc_u32 s13, s13, 0
	v_lshl_add_u64 v[136:137], v[44:45], 0, s[12:13]
	global_load_dword v120, v[136:137], off nt
	v_lshl_add_u64 v[138:139], v[42:43], 0, s[12:13]
	global_load_dword v121, v[138:139], off nt
	v_lshl_add_u64 v[136:137], v[40:41], 0, s[12:13]
	global_load_dword v122, v[136:137], off nt
	v_lshl_add_u64 v[138:139], v[38:39], 0, s[12:13]
	global_load_dword v123, v[138:139], off nt
	v_lshl_add_u64 v[136:137], v[8:9], 0, s[12:13]
	global_load_dword v124, v[136:137], off nt
	v_lshl_add_u64 v[138:139], v[6:7], 0, s[12:13]
	global_load_dword v125, v[138:139], off nt
	v_lshl_add_u64 v[136:137], v[4:5], 0, s[12:13]
	global_load_dword v126, v[136:137], off nt
	v_lshl_add_u64 v[138:139], v[2:3], 0, s[12:13]
	global_load_dword v127, v[138:139], off nt
	s_add_u32 s12, s12, 0x10000
	s_addc_u32 s13, s13, 0
	v_lshl_add_u64 v[136:137], v[44:45], 0, s[12:13]
	global_load_dword v128, v[136:137], off nt
	v_lshl_add_u64 v[138:139], v[42:43], 0, s[12:13]
	global_load_dword v129, v[138:139], off nt
	v_lshl_add_u64 v[136:137], v[40:41], 0, s[12:13]
	global_load_dword v130, v[136:137], off nt
	v_lshl_add_u64 v[138:139], v[38:39], 0, s[12:13]
	global_load_dword v131, v[138:139], off nt
	v_lshl_add_u64 v[136:137], v[8:9], 0, s[12:13]
	global_load_dword v132, v[136:137], off nt
	v_lshl_add_u64 v[138:139], v[6:7], 0, s[12:13]
	global_load_dword v133, v[138:139], off nt
	v_lshl_add_u64 v[136:137], v[4:5], 0, s[12:13]
	global_load_dword v134, v[136:137], off nt
	v_lshl_add_u64 v[138:139], v[2:3], 0, s[12:13]
	global_load_dword v135, v[138:139], off nt
	s_add_u32 s12, s12, 0x10000
	s_addc_u32 s13, s13, 0
	v_lshl_add_u64 v[46:47], v[44:45], 0, s[12:13]
	v_lshl_add_u64 v[48:49], v[42:43], 0, s[12:13]
	v_lshl_add_u64 v[50:51], v[40:41], 0, s[12:13]
	v_lshl_add_u64 v[94:95], v[38:39], 0, s[12:13]
	v_lshl_add_u64 v[96:97], v[8:9], 0, s[12:13]
	v_lshl_add_u64 v[98:99], v[6:7], 0, s[12:13]
	v_lshl_add_u64 v[100:101], v[4:5], 0, s[12:13]
	v_lshl_add_u64 v[102:103], v[2:3], 0, s[12:13]
	global_load_dword v46, v[46:47], off nt
	s_nop 0
	global_load_dword v47, v[48:49], off nt
	s_nop 0
	global_load_dword v48, v[50:51], off nt
	global_load_dword v49, v[94:95], off nt
	s_nop 0
	global_load_dword v50, v[96:97], off nt
	global_load_dword v51, v[98:99], off nt
	global_load_dword v94, v[100:101], off nt
	global_load_dword v95, v[102:103], off nt
	s_add_u32 s12, s12, 0x10000
	s_addc_u32 s13, s13, 0
	v_add_u32_e32 v96, 0x400, v0
	s_waitcnt vmcnt(30)
	ds_write2_b32 v0, v112, v113 offset1:66
	s_waitcnt vmcnt(28)
	ds_write2_b32 v0, v114, v115 offset0:132 offset1:198
	s_waitcnt vmcnt(26)
	ds_write2_b32 v96, v116, v117 offset0:8 offset1:74
	s_waitcnt vmcnt(24)
	ds_write2_b32 v96, v118, v119 offset0:140 offset1:206
	v_add_u32_e32 v0, 0x840, v0
	v_add_u32_e32 v96, 0x400, v0
	s_waitcnt vmcnt(22)
	ds_write2_b32 v0, v120, v121 offset1:66
	s_waitcnt vmcnt(20)
	ds_write2_b32 v0, v122, v123 offset0:132 offset1:198
	s_waitcnt vmcnt(18)
	ds_write2_b32 v96, v124, v125 offset0:8 offset1:74
	s_waitcnt vmcnt(16)
	ds_write2_b32 v96, v126, v127 offset0:140 offset1:206
	v_add_u32_e32 v0, 0x840, v0
	v_add_u32_e32 v96, 0x400, v0
	s_waitcnt vmcnt(14)
	ds_write2_b32 v0, v128, v129 offset1:66
	s_waitcnt vmcnt(12)
	ds_write2_b32 v0, v130, v131 offset0:132 offset1:198
	s_waitcnt vmcnt(10)
	ds_write2_b32 v96, v132, v133 offset0:8 offset1:74
	s_waitcnt vmcnt(8)
	ds_write2_b32 v96, v134, v135 offset0:140 offset1:206
	v_add_u32_e32 v0, 0x840, v0
	v_add_u32_e32 v96, 0x400, v0
	s_waitcnt vmcnt(6)
	ds_write2_b32 v0, v46, v47 offset1:66
	s_waitcnt vmcnt(4)
	ds_write2_b32 v0, v48, v49 offset0:132 offset1:198
	s_waitcnt vmcnt(2)
	ds_write2_b32 v96, v50, v51 offset0:8 offset1:74
	s_waitcnt vmcnt(0)
	ds_write2_b32 v96, v94, v95 offset0:140 offset1:206
	v_add_u32_e32 v0, 0x840, v0
	s_waitcnt lgkmcnt(0)
	v_lshlrev_b32_e32 v0, 1, v93
	ds_read2_b32 v[6:7], v52 offset0:33 offset1:41
	ds_read2_b32 v[8:9], v52 offset1:8
	ds_read2_b32 v[38:39], v52 offset0:66 offset1:74
	ds_read2_b32 v[40:41], v52 offset0:99 offset1:107
	ds_read2_b32 v[42:43], v52 offset0:132 offset1:140
	ds_read2_b32 v[44:45], v52 offset0:165 offset1:173
	ds_read2_b32 v[46:47], v52 offset0:198 offset1:206
	ds_read2_b32 v[48:49], v52 offset0:231 offset1:239
	v_and_b32_e32 v0, 0x1fc0, v0
	v_lshlrev_b32_e32 v2, 5, v93
	v_add_u32_e32 v0, 0xffffec00, v0
	v_and_b32_e32 v96, 0x3e0, v2
	v_lshl_add_u64 v[50:51], v[0:1], 1, v[22:23]
	v_or_b32_e32 v0, v96, v29
	v_lshlrev_b32_e32 v0, 11, v0
	s_waitcnt lgkmcnt(6)
	v_cvt_pk_bf16_f32 v2, v8, v6
	s_waitcnt lgkmcnt(4)
	v_cvt_pk_bf16_f32 v3, v38, v40
	s_waitcnt lgkmcnt(2)
	v_cvt_pk_bf16_f32 v4, v42, v44
	s_waitcnt lgkmcnt(0)
	v_cvt_pk_bf16_f32 v5, v46, v48
	v_lshl_add_u64 v[94:95], v[50:51], 0, v[0:1]
	global_store_dwordx4 v[94:95], v[2:5], off
	v_or_b32_e32 v0, v96, v53
	v_lshlrev_b32_e32 v0, 11, v0
	v_cvt_pk_bf16_f32 v2, v9, v7
	v_cvt_pk_bf16_f32 v3, v39, v41
	v_cvt_pk_bf16_f32 v4, v43, v45
	v_cvt_pk_bf16_f32 v5, v47, v49
	ds_read2_b32 v[8:9], v52 offset0:49 offset1:57
	ds_read2_b32 v[38:39], v52 offset0:16 offset1:24
	ds_read2_b32 v[40:41], v52 offset0:82 offset1:90
	ds_read2_b32 v[42:43], v52 offset0:115 offset1:123
	ds_read2_b32 v[44:45], v52 offset0:148 offset1:156
	ds_read2_b32 v[46:47], v52 offset0:181 offset1:189
	ds_read2_b32 v[48:49], v52 offset0:214 offset1:222
	ds_read2_b32 v[94:95], v52 offset0:247 offset1:255
	v_lshl_add_u64 v[6:7], v[50:51], 0, v[0:1]
	v_or_b32_e32 v0, v96, v54
	v_lshlrev_b32_e32 v0, 11, v0
	global_store_dwordx4 v[6:7], v[2:5], off
	v_lshl_add_u64 v[6:7], v[50:51], 0, v[0:1]
	v_or_b32_e32 v0, v96, v55
	s_waitcnt lgkmcnt(6)
	v_cvt_pk_bf16_f32 v2, v38, v8
	s_waitcnt lgkmcnt(4)
	v_cvt_pk_bf16_f32 v3, v40, v42
	s_waitcnt lgkmcnt(2)
	v_cvt_pk_bf16_f32 v4, v44, v46
	s_waitcnt lgkmcnt(0)
	v_cvt_pk_bf16_f32 v5, v48, v94
	v_lshlrev_b32_e32 v0, 11, v0
	global_store_dwordx4 v[6:7], v[2:5], off
	v_lshl_add_u64 v[6:7], v[50:51], 0, v[0:1]
	s_nop 0
	v_cvt_pk_bf16_f32 v2, v39, v9
	v_cvt_pk_bf16_f32 v3, v41, v43
	v_cvt_pk_bf16_f32 v4, v45, v47
	v_cvt_pk_bf16_f32 v5, v49, v95
	global_store_dwordx4 v[6:7], v[2:5], off
	s_waitcnt lgkmcnt(0)

; __device__ __forceinline__ void tr_item(const float* W, int N, int Klim, int k0, int n0, bf16* WT, int ldk, int drow, int dcol, const float* sc, float* scr, int lane, const float* sc2 = nullptr, bool nts = true) {
;     if (k0 + 64 <= Klim) {
; #pragma unroll 8
;         for (int i = 0; i < 32; ++i) { const int kk = 2 * i + (lane >> 5); scr[kk * 33 + (lane & 31)] = __builtin_nontemporal_load(W + (size_t)(k0 + kk) * N + n0 + (lane & 31)); }
;     } else {
; #pragma unroll 8
;         for (int i = 0; i < 32; ++i) { const int kk = 2 * i + (lane >> 5); const int k = k0 + kk; float v = 0.f; if (k < Klim) v = W[(size_t)k * N + n0 + (lane & 31)]; scr[kk * 33 + (lane & 31)] = v; }
;     }
;     asm volatile("s_waitcnt lgkmcnt(0)" ::: "memory");
;     const int c = lane & 7;
;     f32x4_t sa = (f32x4_t){1.f, 1.f, 1.f, 1.f}, sb = sa;
;     if (sc) { sa = *(const f32x4_t*)(sc + k0 + 8 * c); sb = *(const f32x4_t*)(sc + k0 + 8 * c + 4);
.LBB0_924:
	v_lshl_add_u64 v[136:137], v[48:49], 0, s[22:23]
	global_load_dword v112, v[136:137], off nt
	v_lshl_add_u64 v[138:139], v[46:47], 0, s[22:23]
	global_load_dword v113, v[138:139], off nt
	v_lshl_add_u64 v[136:137], v[44:45], 0, s[22:23]
	global_load_dword v114, v[136:137], off nt
	v_lshl_add_u64 v[138:139], v[42:43], 0, s[22:23]
	global_load_dword v115, v[138:139], off nt
	v_lshl_add_u64 v[136:137], v[8:9], 0, s[22:23]
	global_load_dword v116, v[136:137], off nt
	v_lshl_add_u64 v[138:139], v[6:7], 0, s[22:23]
	global_load_dword v117, v[138:139], off nt
	v_lshl_add_u64 v[136:137], v[4:5], 0, s[22:23]
	global_load_dword v118, v[136:137], off nt
	v_lshl_add_u64 v[138:139], v[2:3], 0, s[22:23]
	global_load_dword v119, v[138:139], off nt
	s_add_u32 s22, s22, 0x50000
	s_addc_u32 s23, s23, 0
	v_lshl_add_u64 v[136:137], v[48:49], 0, s[22:23]
	global_load_dword v120, v[136:137], off nt
	v_lshl_add_u64 v[138:139], v[46:47], 0, s[22:23]
	global_load_dword v121, v[138:139], off nt
	v_lshl_add_u64 v[136:137], v[44:45], 0, s[22:23]
	global_load_dword v122, v[136:137], off nt
	v_lshl_add_u64 v[138:139], v[42:43], 0, s[22:23]
	global_load_dword v123, v[138:139], off nt
	v_lshl_add_u64 v[136:137], v[8:9], 0, s[22:23]
	global_load_dword v124, v[136:137], off nt
	v_lshl_add_u64 v[138:139], v[6:7], 0, s[22:23]
	global_load_dword v125, v[138:139], off nt
	v_lshl_add_u64 v[136:137], v[4:5], 0, s[22:23]
	global_load_dword v126, v[136:137], off nt
	v_lshl_add_u64 v[138:139], v[2:3], 0, s[22:23]
	global_load_dword v127, v[138:139], off nt
	s_add_u32 s22, s22, 0x50000
	s_addc_u32 s23, s23, 0
	v_lshl_add_u64 v[136:137], v[48:49], 0, s[22:23]
	global_load_dword v128, v[136:137], off nt
	v_lshl_add_u64 v[138:139], v[46:47], 0, s[22:23]
	global_load_dword v129, v[138:139], off nt
	v_lshl_add_u64 v[136:137], v[44:45], 0, s[22:23]
	global_load_dword v130, v[136:137], off nt
	v_lshl_add_u64 v[138:139], v[42:43], 0, s[22:23]
	global_load_dword v131, v[138:139], off nt
	v_lshl_add_u64 v[136:137], v[8:9], 0, s[22:23]
	global_load_dword v132, v[136:137], off nt
	v_lshl_add_u64 v[138:139], v[6:7], 0, s[22:23]
	global_load_dword v133, v[138:139], off nt
	v_lshl_add_u64 v[136:137], v[4:5], 0, s[22:23]
	global_load_dword v134, v[136:137], off nt
	v_lshl_add_u64 v[138:139], v[2:3], 0, s[22:23]
	global_load_dword v135, v[138:139], off nt
	s_add_u32 s22, s22, 0x50000
	s_addc_u32 s23, s23, 0
	v_lshl_add_u64 v[50:51], v[48:49], 0, s[22:23]
	v_lshl_add_u64 v[94:95], v[46:47], 0, s[22:23]
	v_lshl_add_u64 v[96:97], v[44:45], 0, s[22:23]
	v_lshl_add_u64 v[98:99], v[42:43], 0, s[22:23]
	v_lshl_add_u64 v[100:101], v[8:9], 0, s[22:23]
	v_lshl_add_u64 v[102:103], v[6:7], 0, s[22:23]
	v_lshl_add_u64 v[104:105], v[4:5], 0, s[22:23]
	v_lshl_add_u64 v[106:107], v[2:3], 0, s[22:23]
	global_load_dword v39, v[50:51], off nt
	s_nop 0
	global_load_dword v50, v[94:95], off nt
	global_load_dword v51, v[96:97], off nt
	s_nop 0
	global_load_dword v94, v[98:99], off nt
	global_load_dword v95, v[100:101], off nt
	global_load_dword v96, v[102:103], off nt
	global_load_dword v97, v[104:105], off nt
	s_nop 0
	global_load_dword v98, v[106:107], off nt
	s_add_u32 s22, s22, 0x50000
	s_addc_u32 s23, s23, 0
	v_add_u32_e32 v99, 0x400, v0
	s_waitcnt vmcnt(30)
	ds_write2_b32 v0, v112, v113 offset1:66
	s_waitcnt vmcnt(28)
	ds_write2_b32 v0, v114, v115 offset0:132 offset1:198
	s_waitcnt vmcnt(26)
	ds_write2_b32 v99, v116, v117 offset0:8 offset1:74
	s_waitcnt vmcnt(24)
	ds_write2_b32 v99, v118, v119 offset0:140 offset1:206
	v_add_u32_e32 v0, 0x840, v0
	v_add_u32_e32 v99, 0x400, v0
	s_waitcnt vmcnt(22)
	ds_write2_b32 v0, v120, v121 offset1:66
	s_waitcnt vmcnt(20)
	ds_write2_b32 v0, v122, v123 offset0:132 offset1:198
	s_waitcnt vmcnt(18)
	ds_write2_b32 v99, v124, v125 offset0:8 offset1:74
	s_waitcnt vmcnt(16)
	ds_write2_b32 v99, v126, v127 offset0:140 offset1:206
	v_add_u32_e32 v0, 0x840, v0
	v_add_u32_e32 v99, 0x400, v0
	s_waitcnt vmcnt(14)
	ds_write2_b32 v0, v128, v129 offset1:66
	s_waitcnt vmcnt(12)
	ds_write2_b32 v0, v130, v131 offset0:132 offset1:198
	s_waitcnt vmcnt(10)
	ds_write2_b32 v99, v132, v133 offset0:8 offset1:74
	s_waitcnt vmcnt(8)
	ds_write2_b32 v99, v134, v135 offset0:140 offset1:206
	v_add_u32_e32 v0, 0x840, v0
	v_add_u32_e32 v99, 0x400, v0
	s_waitcnt vmcnt(6)
	ds_write2_b32 v0, v39, v50 offset1:66
	s_waitcnt vmcnt(4)
	ds_write2_b32 v0, v51, v94 offset0:132 offset1:198
	s_waitcnt vmcnt(2)
	ds_write2_b32 v99, v95, v96 offset0:8 offset1:74
	s_waitcnt vmcnt(0)
	ds_write2_b32 v99, v97, v98 offset0:140 offset1:206
	v_add_u32_e32 v0, 0x840, v0
	s_waitcnt lgkmcnt(0)
	s_cmp_eq_u64 s[12:13], 0
	s_cbranch_scc0 .LBB0_756
	v_mov_b32_e32 v2, 1.0
	v_mov_b32_e32 v3, v2
	v_mov_b32_e32 v4, v2
	v_mov_b32_e32 v5, v2
	v_mov_b32_e32 v6, v2
	v_mov_b32_e32 v7, v2
	v_mov_b32_e32 v8, v2
	v_mov_b32_e32 v9, v2
	s_branch .LBB0_757
